# write-through stores in the prologue phases and the final norm phase (smaller L2 write-back at their seams and at kernel end)
# speedup vs baseline: 1.0073x; 1.0073x over previous
.LBB0_24:
	s_mul_hi_i32 s0, s14, 0x30c30c31
	s_lshr_b32 s4, s0, 31
	s_ashr_i32 s0, s0, 9
	s_add_i32 s4, s0, s4
	s_mul_i32 s0, s4, 0xfffff580
	s_add_i32 s0, s14, s0
	s_cmpk_gt_i32 s0, 0x17f
	s_mov_b64 s[8:9], -1
	s_cbranch_scc0 .LBB0_34
	s_ashr_i32 s5, s4, 31
	s_cmpk_gt_u32 s0, 0x27f
	s_cbranch_scc0 .LBB0_31
	s_lshl_b64 s[10:11], s[4:5], 24
	s_lshl_b64 s[8:9], s[4:5], 23
	s_cmpk_gt_u32 s0, 0x67f
	s_mov_b64 s[12:13], -1
	s_cbranch_scc0 .LBB0_28
	s_add_u32 s13, s94, s10
	s_addc_u32 s71, s95, s11
	s_add_u32 s72, s50, s8
	s_mul_i32 s12, s4, 0xffffd600
	s_addc_u32 s73, s51, s9
	s_add_i32 s12, s38, s12
	s_add_i32 s12, s12, 0x3e600
	s_and_b32 s74, s12, 0x3ffc0
	s_and_b32 s12, s36, 0x3c0
	s_lshl_b32 s70, s12, 2
	s_add_u32 s70, s13, s70
	v_or_b32_e32 v2, s74, v1
	s_addc_u32 s71, s71, 0
	v_mov_b32_e32 v9, v3
	v_lshl_add_u64 v[56:57], s[70:71], 0, v[8:9]
	v_lshlrev_b32_e32 v2, 12, v2
	v_lshl_add_u64 v[116:117], v[56:57], 0, v[2:3]
	v_add_co_u32_e32 v60, vcc, s40, v116
	s_lshl_b32 s13, s74, 1
	s_nop 0
	v_addc_co_u32_e32 v61, vcc, 0, v117, vcc
	v_add_co_u32_e32 v64, vcc, s41, v116
	global_load_dwordx4 v[56:59], v[116:117], off
	s_nop 0
	global_load_dwordx4 v[60:63], v[60:61], off
	v_addc_co_u32_e32 v65, vcc, 0, v117, vcc
	v_add_co_u32_e32 v68, vcc, s42, v116
	s_add_u32 s70, s72, s13
	s_nop 0
	v_addc_co_u32_e32 v69, vcc, 0, v117, vcc
	v_add_co_u32_e32 v72, vcc, s43, v116
	global_load_dwordx4 v[64:67], v[64:65], off
	s_nop 0
	global_load_dwordx4 v[68:71], v[68:69], off
	v_addc_co_u32_e32 v73, vcc, 0, v117, vcc
	v_add_co_u32_e32 v76, vcc, s44, v116
	s_addc_u32 s71, s73, 0
	s_nop 0
	v_addc_co_u32_e32 v77, vcc, 0, v117, vcc
	v_add_co_u32_e32 v80, vcc, s45, v116
	global_load_dwordx4 v[72:75], v[72:73], off
	s_nop 0
	global_load_dwordx4 v[76:79], v[76:77], off
	v_addc_co_u32_e32 v81, vcc, 0, v117, vcc
	v_add_co_u32_e32 v84, vcc, s52, v116
	v_mov_b32_e32 v11, v3
	s_nop 0
	v_addc_co_u32_e32 v85, vcc, 0, v117, vcc
	v_add_co_u32_e32 v88, vcc, s53, v116
	global_load_dwordx4 v[80:83], v[80:81], off
	s_nop 0
	global_load_dwordx4 v[84:87], v[84:85], off
	v_addc_co_u32_e32 v89, vcc, 0, v117, vcc
	v_add_co_u32_e32 v92, vcc, s54, v116
	v_or_b32_e32 v2, s12, v13
	s_nop 0
	v_addc_co_u32_e32 v93, vcc, 0, v117, vcc
	v_add_co_u32_e32 v96, vcc, s55, v116
	global_load_dwordx4 v[88:91], v[88:89], off
	s_nop 0
	global_load_dwordx4 v[92:95], v[92:93], off
	v_addc_co_u32_e32 v97, vcc, 0, v117, vcc
	v_add_co_u32_e32 v100, vcc, s60, v116
	v_lshlrev_b32_e32 v2, 13, v2
	s_nop 0
	v_addc_co_u32_e32 v101, vcc, 0, v117, vcc
	v_add_co_u32_e32 v104, vcc, s61, v116
	global_load_dwordx4 v[96:99], v[96:97], off
	s_nop 0
	global_load_dwordx4 v[100:103], v[100:101], off
	v_addc_co_u32_e32 v105, vcc, 0, v117, vcc
	v_add_co_u32_e32 v108, vcc, s62, v116
	s_nop 1
	v_addc_co_u32_e32 v109, vcc, 0, v117, vcc
	global_load_dwordx4 v[104:107], v[104:105], off
	s_nop 0
	global_load_dwordx4 v[108:111], v[108:109], off
	v_add_co_u32_e32 v112, vcc, s63, v116
	s_nop 1
	v_addc_co_u32_e32 v113, vcc, 0, v117, vcc
	global_load_dwordx4 v[112:115], v[112:113], off
	v_add_co_u32_e32 v116, vcc, s65, v116
	s_nop 1
	v_addc_co_u32_e32 v117, vcc, 0, v117, vcc
	global_load_dwordx4 v[116:119], v[116:117], off
	s_waitcnt vmcnt(15)
	ds_write2_b32 v12, v56, v57 offset1:1
	ds_write2_b32 v12, v58, v59 offset0:2 offset1:3
	s_waitcnt vmcnt(14)
	ds_write2_b32 v22, v60, v61 offset1:1
	ds_write2_b32 v23, v62, v63 offset1:1
	s_waitcnt vmcnt(13)
	ds_write2_b32 v24, v64, v65 offset1:1
	ds_write2_b32 v25, v66, v67 offset1:1
	s_waitcnt vmcnt(12)
	ds_write2_b32 v26, v68, v69 offset1:1
	ds_write2_b32 v27, v70, v71 offset1:1
	s_waitcnt vmcnt(11)
	ds_write2_b32 v28, v72, v73 offset1:1
	ds_write2_b32 v29, v74, v75 offset1:1
	s_waitcnt vmcnt(10)
	ds_write2_b32 v30, v76, v77 offset1:1
	ds_write2_b32 v31, v78, v79 offset1:1
	s_waitcnt vmcnt(9)
	ds_write2_b32 v32, v80, v81 offset1:1
	ds_write2_b32 v33, v82, v83 offset1:1
	s_waitcnt vmcnt(8)
	ds_write2_b32 v34, v84, v85 offset1:1
	ds_write2_b32 v35, v86, v87 offset1:1
	s_waitcnt vmcnt(7)
	ds_write2_b32 v36, v88, v89 offset1:1
	ds_write2_b32 v37, v90, v91 offset1:1
	s_waitcnt vmcnt(6)
	ds_write2_b32 v38, v92, v93 offset1:1
	ds_write2_b32 v39, v94, v95 offset1:1
	s_waitcnt vmcnt(5)
	ds_write2_b32 v40, v96, v97 offset1:1
	ds_write2_b32 v41, v98, v99 offset1:1
	s_waitcnt vmcnt(4)
	ds_write2_b32 v42, v100, v101 offset1:1
	ds_write2_b32 v43, v102, v103 offset1:1
	s_waitcnt vmcnt(3)
	ds_write2_b32 v44, v104, v105 offset1:1
	ds_write2_b32 v45, v106, v107 offset1:1
	s_waitcnt vmcnt(2)
	ds_write2_b32 v46, v108, v109 offset1:1
	ds_write2_b32 v47, v110, v111 offset1:1
	s_waitcnt vmcnt(1)
	ds_write2_b32 v48, v112, v113 offset1:1
	ds_write2_b32 v49, v114, v115 offset1:1
	s_waitcnt vmcnt(0)
	ds_write2_b32 v51, v116, v117 offset1:1
	ds_write2_b32 v52, v118, v119 offset1:1
	s_waitcnt lgkmcnt(0)
	ds_read2_b32 v[60:61], v14 offset0:65 offset1:73
	ds_read2_b32 v[62:63], v14 offset1:8
	ds_read2_b32 v[64:65], v14 offset0:130 offset1:138
	ds_read2_b32 v[66:67], v14 offset0:195 offset1:203
	ds_read2_b32 v[68:69], v53 offset0:4 offset1:12
	ds_read2_b32 v[70:71], v53 offset0:69 offset1:77
	ds_read2_b32 v[72:73], v53 offset0:134 offset1:142
	ds_read2_b32 v[74:75], v53 offset0:199 offset1:207
	v_lshl_add_u64 v[76:77], s[70:71], 0, v[10:11]
	s_waitcnt lgkmcnt(6)
	v_cvt_pk_bf16_f32 v56, v62, v60
	s_waitcnt lgkmcnt(4)
	v_cvt_pk_bf16_f32 v57, v64, v66
	s_waitcnt lgkmcnt(2)
	v_cvt_pk_bf16_f32 v58, v68, v70
	s_waitcnt lgkmcnt(0)
	v_cvt_pk_bf16_f32 v59, v72, v74
	v_lshl_add_u64 v[78:79], v[76:77], 0, v[2:3]
	global_store_dwordx4 v[78:79], v[56:59], off sc1
	v_or_b32_e32 v2, s12, v15
	v_lshlrev_b32_e32 v2, 13, v2
	v_cvt_pk_bf16_f32 v56, v63, v61
	v_cvt_pk_bf16_f32 v57, v65, v67
	v_cvt_pk_bf16_f32 v58, v69, v71
	v_cvt_pk_bf16_f32 v59, v73, v75
	ds_read2_b32 v[62:63], v14 offset0:81 offset1:89
	ds_read2_b32 v[64:65], v14 offset0:16 offset1:24
	ds_read2_b32 v[66:67], v14 offset0:146 offset1:154
	ds_read2_b32 v[68:69], v14 offset0:211 offset1:219
	ds_read2_b32 v[70:71], v53 offset0:20 offset1:28
	ds_read2_b32 v[72:73], v53 offset0:85 offset1:93
	ds_read2_b32 v[74:75], v53 offset0:150 offset1:158
	ds_read2_b32 v[78:79], v53 offset0:215 offset1:223
	v_lshl_add_u64 v[60:61], v[76:77], 0, v[2:3]
	v_or_b32_e32 v2, s12, v16
	v_lshlrev_b32_e32 v2, 13, v2
	global_store_dwordx4 v[60:61], v[56:59], off sc1
	v_lshl_add_u64 v[60:61], v[76:77], 0, v[2:3]
	v_or_b32_e32 v2, s12, v17
	s_waitcnt lgkmcnt(6)
	v_cvt_pk_bf16_f32 v56, v64, v62
	s_waitcnt lgkmcnt(4)
	v_cvt_pk_bf16_f32 v57, v66, v68
	s_waitcnt lgkmcnt(2)
	v_cvt_pk_bf16_f32 v58, v70, v72
	s_waitcnt lgkmcnt(0)
	v_cvt_pk_bf16_f32 v59, v74, v78
	global_store_dwordx4 v[60:61], v[56:59], off sc1
	v_lshlrev_b32_e32 v2, 13, v2
	v_lshl_add_u64 v[60:61], v[76:77], 0, v[2:3]
	v_cvt_pk_bf16_f32 v56, v65, v63
	v_cvt_pk_bf16_f32 v57, v67, v69
	v_cvt_pk_bf16_f32 v58, v71, v73
	v_cvt_pk_bf16_f32 v59, v75, v79
	ds_read2_b32 v[62:63], v14 offset0:32 offset1:40
	ds_read2_b32 v[64:65], v14 offset0:97 offset1:105
	ds_read2_b32 v[66:67], v14 offset0:162 offset1:170
	ds_read2_b32 v[68:69], v14 offset0:227 offset1:235
	ds_read2_b32 v[70:71], v53 offset0:36 offset1:44
	ds_read2_b32 v[72:73], v53 offset0:101 offset1:109
	ds_read2_b32 v[74:75], v53 offset0:166 offset1:174
	ds_read2_b32 v[78:79], v53 offset0:231 offset1:239
	v_or_b32_e32 v2, s12, v18
	v_lshlrev_b32_e32 v2, 13, v2
	global_store_dwordx4 v[60:61], v[56:59], off sc1
	v_lshl_add_u64 v[60:61], v[76:77], 0, v[2:3]
	v_or_b32_e32 v2, s12, v19
	s_waitcnt lgkmcnt(6)
	v_cvt_pk_bf16_f32 v56, v62, v64
	s_waitcnt lgkmcnt(4)
	v_cvt_pk_bf16_f32 v57, v66, v68
	s_waitcnt lgkmcnt(2)
	v_cvt_pk_bf16_f32 v58, v70, v72
	s_waitcnt lgkmcnt(0)
	v_cvt_pk_bf16_f32 v59, v74, v78
	global_store_dwordx4 v[60:61], v[56:59], off sc1
	v_lshlrev_b32_e32 v2, 13, v2
	v_lshl_add_u64 v[60:61], v[76:77], 0, v[2:3]
	v_cvt_pk_bf16_f32 v56, v63, v65
	v_cvt_pk_bf16_f32 v57, v67, v69
	v_cvt_pk_bf16_f32 v58, v71, v73
	v_cvt_pk_bf16_f32 v59, v75, v79
	ds_read2_b32 v[62:63], v14 offset0:48 offset1:56
	ds_read2_b32 v[64:65], v14 offset0:113 offset1:121
	ds_read2_b32 v[66:67], v14 offset0:178 offset1:186
	ds_read2_b32 v[68:69], v14 offset0:243 offset1:251
	ds_read2_b32 v[70:71], v53 offset0:52 offset1:60
	ds_read2_b32 v[72:73], v53 offset0:117 offset1:125
	ds_read2_b32 v[74:75], v53 offset0:182 offset1:190
	ds_read2_b32 v[78:79], v53 offset0:247 offset1:255
	v_or_b32_e32 v2, s12, v20
	v_lshlrev_b32_e32 v2, 13, v2
	global_store_dwordx4 v[60:61], v[56:59], off sc1
	v_lshl_add_u64 v[60:61], v[76:77], 0, v[2:3]
	v_or_b32_e32 v2, s12, v21
	s_waitcnt lgkmcnt(6)
	v_cvt_pk_bf16_f32 v56, v62, v64
	s_waitcnt lgkmcnt(4)
	v_cvt_pk_bf16_f32 v57, v66, v68
	s_waitcnt lgkmcnt(2)
	v_cvt_pk_bf16_f32 v58, v70, v72
	s_waitcnt lgkmcnt(0)
	v_cvt_pk_bf16_f32 v59, v74, v78
	v_lshlrev_b32_e32 v2, 13, v2
	global_store_dwordx4 v[60:61], v[56:59], off sc1
	v_lshl_add_u64 v[60:61], v[76:77], 0, v[2:3]
	s_mov_b64 s[12:13], 0
	v_cvt_pk_bf16_f32 v56, v63, v65
	v_cvt_pk_bf16_f32 v57, v67, v69
	v_cvt_pk_bf16_f32 v58, v71, v73
	v_cvt_pk_bf16_f32 v59, v75, v79
	global_store_dwordx4 v[60:61], v[56:59], off sc1
	s_waitcnt lgkmcnt(0)
.LBB0_28:
	s_andn2_b64 vcc, exec, s[12:13]
	s_cbranch_vccnz .LBB0_30
	s_add_u32 s10, s92, s10
	s_addc_u32 s11, s93, s11
	s_add_u32 s12, s56, s8
	s_addc_u32 s9, s57, s9
	s_add_i32 s8, s0, 0xfd80
	s_and_b32 s13, s8, 0xffc0
	s_and_b32 s8, s36, 0xfc0
	s_lshl_b32 s70, s8, 2
	s_add_u32 s10, s10, s70
	v_or_b32_e32 v2, s13, v1
	s_addc_u32 s11, s11, 0
	v_mov_b32_e32 v9, v3
	v_lshl_add_u64 v[56:57], s[10:11], 0, v[8:9]
	v_lshlrev_b32_e32 v2, 14, v2
	v_lshl_add_u64 v[116:117], v[56:57], 0, v[2:3]
	v_add_co_u32_e32 v60, vcc, s43, v116
	s_mov_b32 s10, 0x40000
	s_nop 0
	v_addc_co_u32_e32 v61, vcc, 0, v117, vcc
	v_add_co_u32_e32 v64, vcc, s53, v116
	global_load_dwordx4 v[56:59], v[116:117], off
	s_nop 0
	global_load_dwordx4 v[60:63], v[60:61], off
	v_addc_co_u32_e32 v65, vcc, 0, v117, vcc
	v_add_co_u32_e32 v68, vcc, s61, v116
	v_mov_b32_e32 v11, v3
	s_nop 0
	v_addc_co_u32_e32 v69, vcc, 0, v117, vcc
	v_add_co_u32_e32 v72, vcc, s10, v116
	s_mov_b32 s10, 0x50000
	s_nop 0
	v_addc_co_u32_e32 v73, vcc, 0, v117, vcc
	v_add_co_u32_e32 v76, vcc, s10, v116
	s_mov_b32 s10, 0x60000
	s_nop 0
	v_addc_co_u32_e32 v77, vcc, 0, v117, vcc
	v_add_co_u32_e32 v80, vcc, s10, v116
	s_mov_b32 s10, 0x70000
	s_nop 0
	v_addc_co_u32_e32 v81, vcc, 0, v117, vcc
	v_add_co_u32_e32 v84, vcc, s10, v116
	s_mov_b32 s10, 0x80000
	s_nop 0
	v_addc_co_u32_e32 v85, vcc, 0, v117, vcc
	v_add_co_u32_e32 v88, vcc, s10, v116
	s_mov_b32 s10, 0x90000
	s_nop 0
	v_addc_co_u32_e32 v89, vcc, 0, v117, vcc
	v_add_co_u32_e32 v92, vcc, s10, v116
	s_mov_b32 s10, 0xa0000
	s_nop 0
	v_addc_co_u32_e32 v93, vcc, 0, v117, vcc
	v_add_co_u32_e32 v96, vcc, s10, v116
	s_mov_b32 s10, 0xb0000
	s_nop 0
	v_addc_co_u32_e32 v97, vcc, 0, v117, vcc
	v_add_co_u32_e32 v100, vcc, s10, v116
	s_mov_b32 s10, 0xc0000
	s_nop 0
	v_addc_co_u32_e32 v101, vcc, 0, v117, vcc
	v_add_co_u32_e32 v104, vcc, s10, v116
	s_mov_b32 s10, 0xd0000
	s_nop 0
	v_addc_co_u32_e32 v105, vcc, 0, v117, vcc
	v_add_co_u32_e32 v108, vcc, s10, v116
	global_load_dwordx4 v[64:67], v[64:65], off
	s_nop 0
	global_load_dwordx4 v[68:71], v[68:69], off
	v_addc_co_u32_e32 v109, vcc, 0, v117, vcc
	global_load_dwordx4 v[72:75], v[72:73], off
	s_nop 0
	global_load_dwordx4 v[76:79], v[76:77], off
	s_nop 0
	global_load_dwordx4 v[80:83], v[80:81], off
	s_nop 0
	global_load_dwordx4 v[84:87], v[84:85], off
	s_nop 0
	global_load_dwordx4 v[88:91], v[88:89], off
	s_nop 0
	global_load_dwordx4 v[92:95], v[92:93], off
	s_nop 0
	global_load_dwordx4 v[96:99], v[96:97], off
	s_nop 0
	global_load_dwordx4 v[100:103], v[100:101], off
	s_nop 0
	global_load_dwordx4 v[104:107], v[104:105], off
	s_nop 0
	global_load_dwordx4 v[108:111], v[108:109], off
	s_mov_b32 s10, 0xe0000
	v_add_co_u32_e32 v112, vcc, s10, v116
	s_mov_b32 s10, 0xf0000
	s_nop 0
	v_addc_co_u32_e32 v113, vcc, 0, v117, vcc
	global_load_dwordx4 v[112:115], v[112:113], off
	v_add_co_u32_e32 v116, vcc, s10, v116
	s_lshl_b32 s10, s13, 1
	s_nop 0
	v_addc_co_u32_e32 v117, vcc, 0, v117, vcc
	global_load_dwordx4 v[116:119], v[116:117], off
	s_add_u32 s10, s12, s10
	s_addc_u32 s11, s9, 0
	v_or_b32_e32 v2, s8, v13
	v_lshlrev_b32_e32 v2, 11, v2
	s_waitcnt vmcnt(15)
	ds_write2_b32 v12, v56, v57 offset1:1
	ds_write2_b32 v12, v58, v59 offset0:2 offset1:3
	s_waitcnt vmcnt(14)
	ds_write2_b32 v22, v60, v61 offset1:1
	ds_write2_b32 v23, v62, v63 offset1:1
	s_waitcnt vmcnt(13)
	ds_write2_b32 v24, v64, v65 offset1:1
	ds_write2_b32 v25, v66, v67 offset1:1
	s_waitcnt vmcnt(12)
	ds_write2_b32 v26, v68, v69 offset1:1
	ds_write2_b32 v27, v70, v71 offset1:1
	s_waitcnt vmcnt(11)
	ds_write2_b32 v28, v72, v73 offset1:1
	ds_write2_b32 v29, v74, v75 offset1:1
	s_waitcnt vmcnt(10)
	ds_write2_b32 v30, v76, v77 offset1:1
	ds_write2_b32 v31, v78, v79 offset1:1
	s_waitcnt vmcnt(9)
	ds_write2_b32 v32, v80, v81 offset1:1
	ds_write2_b32 v33, v82, v83 offset1:1
	s_waitcnt vmcnt(8)
	ds_write2_b32 v34, v84, v85 offset1:1
	ds_write2_b32 v35, v86, v87 offset1:1
	s_waitcnt vmcnt(7)
	ds_write2_b32 v36, v88, v89 offset1:1
	ds_write2_b32 v37, v90, v91 offset1:1
	s_waitcnt vmcnt(6)
	ds_write2_b32 v38, v92, v93 offset1:1
	ds_write2_b32 v39, v94, v95 offset1:1
	s_waitcnt vmcnt(5)
	ds_write2_b32 v40, v96, v97 offset1:1
	ds_write2_b32 v41, v98, v99 offset1:1
	s_waitcnt vmcnt(4)
	ds_write2_b32 v42, v100, v101 offset1:1
	ds_write2_b32 v43, v102, v103 offset1:1
	s_waitcnt vmcnt(3)
	ds_write2_b32 v44, v104, v105 offset1:1
	ds_write2_b32 v45, v106, v107 offset1:1
	s_waitcnt vmcnt(2)
	ds_write2_b32 v46, v108, v109 offset1:1
	ds_write2_b32 v47, v110, v111 offset1:1
	s_waitcnt vmcnt(1)
	ds_write2_b32 v48, v112, v113 offset1:1
	ds_write2_b32 v49, v114, v115 offset1:1
	s_waitcnt vmcnt(0)
	ds_write2_b32 v51, v116, v117 offset1:1
	ds_write2_b32 v52, v118, v119 offset1:1
	s_waitcnt lgkmcnt(0)
	ds_read2_b32 v[60:61], v14 offset0:65 offset1:73
	ds_read2_b32 v[62:63], v14 offset1:8
	ds_read2_b32 v[64:65], v14 offset0:130 offset1:138
	ds_read2_b32 v[66:67], v14 offset0:195 offset1:203
	ds_read2_b32 v[68:69], v53 offset0:4 offset1:12
	ds_read2_b32 v[70:71], v53 offset0:69 offset1:77
	ds_read2_b32 v[72:73], v53 offset0:134 offset1:142
	ds_read2_b32 v[74:75], v53 offset0:199 offset1:207
	v_lshl_add_u64 v[76:77], s[10:11], 0, v[10:11]
	s_waitcnt lgkmcnt(6)
	v_cvt_pk_bf16_f32 v56, v62, v60
	s_waitcnt lgkmcnt(4)
	v_cvt_pk_bf16_f32 v57, v64, v66
	s_waitcnt lgkmcnt(2)
	v_cvt_pk_bf16_f32 v58, v68, v70
	s_waitcnt lgkmcnt(0)
	v_cvt_pk_bf16_f32 v59, v72, v74
	v_lshl_add_u64 v[78:79], v[76:77], 0, v[2:3]
	global_store_dwordx4 v[78:79], v[56:59], off sc1
	v_or_b32_e32 v2, s8, v15
	v_lshlrev_b32_e32 v2, 11, v2
	v_cvt_pk_bf16_f32 v56, v63, v61
	v_cvt_pk_bf16_f32 v57, v65, v67
	v_cvt_pk_bf16_f32 v58, v69, v71
	v_cvt_pk_bf16_f32 v59, v73, v75
	ds_read2_b32 v[62:63], v14 offset0:81 offset1:89
	ds_read2_b32 v[64:65], v14 offset0:16 offset1:24
	ds_read2_b32 v[66:67], v14 offset0:146 offset1:154
	ds_read2_b32 v[68:69], v14 offset0:211 offset1:219
	ds_read2_b32 v[70:71], v53 offset0:20 offset1:28
	ds_read2_b32 v[72:73], v53 offset0:85 offset1:93
	ds_read2_b32 v[74:75], v53 offset0:150 offset1:158
	ds_read2_b32 v[78:79], v53 offset0:215 offset1:223
	v_lshl_add_u64 v[60:61], v[76:77], 0, v[2:3]
	v_or_b32_e32 v2, s8, v16
	v_lshlrev_b32_e32 v2, 11, v2
	global_store_dwordx4 v[60:61], v[56:59], off sc1
	v_lshl_add_u64 v[60:61], v[76:77], 0, v[2:3]
	v_or_b32_e32 v2, s8, v17
	s_waitcnt lgkmcnt(6)
	v_cvt_pk_bf16_f32 v56, v64, v62
	s_waitcnt lgkmcnt(4)
	v_cvt_pk_bf16_f32 v57, v66, v68
	s_waitcnt lgkmcnt(2)
	v_cvt_pk_bf16_f32 v58, v70, v72
	s_waitcnt lgkmcnt(0)
	v_cvt_pk_bf16_f32 v59, v74, v78
	global_store_dwordx4 v[60:61], v[56:59], off sc1
	v_lshlrev_b32_e32 v2, 11, v2
	v_lshl_add_u64 v[60:61], v[76:77], 0, v[2:3]
	v_cvt_pk_bf16_f32 v56, v65, v63
	v_cvt_pk_bf16_f32 v57, v67, v69
	v_cvt_pk_bf16_f32 v58, v71, v73
	v_cvt_pk_bf16_f32 v59, v75, v79
	ds_read2_b32 v[62:63], v14 offset0:32 offset1:40
	ds_read2_b32 v[64:65], v14 offset0:97 offset1:105
	ds_read2_b32 v[66:67], v14 offset0:162 offset1:170
	ds_read2_b32 v[68:69], v14 offset0:227 offset1:235
	ds_read2_b32 v[70:71], v53 offset0:36 offset1:44
	ds_read2_b32 v[72:73], v53 offset0:101 offset1:109
	ds_read2_b32 v[74:75], v53 offset0:166 offset1:174
	ds_read2_b32 v[78:79], v53 offset0:231 offset1:239
	v_or_b32_e32 v2, s8, v18
	v_lshlrev_b32_e32 v2, 11, v2
	global_store_dwordx4 v[60:61], v[56:59], off sc1
	v_lshl_add_u64 v[60:61], v[76:77], 0, v[2:3]
	v_or_b32_e32 v2, s8, v19
	s_waitcnt lgkmcnt(6)
	v_cvt_pk_bf16_f32 v56, v62, v64
	s_waitcnt lgkmcnt(4)
	v_cvt_pk_bf16_f32 v57, v66, v68
	s_waitcnt lgkmcnt(2)
	v_cvt_pk_bf16_f32 v58, v70, v72
	s_waitcnt lgkmcnt(0)
	v_cvt_pk_bf16_f32 v59, v74, v78
	global_store_dwordx4 v[60:61], v[56:59], off sc1
	v_lshlrev_b32_e32 v2, 11, v2
	v_lshl_add_u64 v[60:61], v[76:77], 0, v[2:3]
	v_cvt_pk_bf16_f32 v56, v63, v65
	v_cvt_pk_bf16_f32 v57, v67, v69
	v_cvt_pk_bf16_f32 v58, v71, v73
	v_cvt_pk_bf16_f32 v59, v75, v79
	ds_read2_b32 v[62:63], v14 offset0:48 offset1:56
	ds_read2_b32 v[64:65], v14 offset0:113 offset1:121
	ds_read2_b32 v[66:67], v14 offset0:178 offset1:186
	ds_read2_b32 v[68:69], v14 offset0:243 offset1:251
	ds_read2_b32 v[70:71], v53 offset0:52 offset1:60
	ds_read2_b32 v[72:73], v53 offset0:117 offset1:125
	ds_read2_b32 v[74:75], v53 offset0:182 offset1:190
	ds_read2_b32 v[78:79], v53 offset0:247 offset1:255
	v_or_b32_e32 v2, s8, v20
	v_lshlrev_b32_e32 v2, 11, v2
	global_store_dwordx4 v[60:61], v[56:59], off sc1
	v_lshl_add_u64 v[60:61], v[76:77], 0, v[2:3]
	v_or_b32_e32 v2, s8, v21
	s_waitcnt lgkmcnt(6)
	v_cvt_pk_bf16_f32 v56, v62, v64
	s_waitcnt lgkmcnt(4)
	v_cvt_pk_bf16_f32 v57, v66, v68
	s_waitcnt lgkmcnt(2)
	v_cvt_pk_bf16_f32 v58, v70, v72
	s_waitcnt lgkmcnt(0)
	v_cvt_pk_bf16_f32 v59, v74, v78
	v_lshlrev_b32_e32 v2, 11, v2
	global_store_dwordx4 v[60:61], v[56:59], off sc1
	v_lshl_add_u64 v[60:61], v[76:77], 0, v[2:3]
	s_nop 0
	v_cvt_pk_bf16_f32 v56, v63, v65
	v_cvt_pk_bf16_f32 v57, v67, v69
	v_cvt_pk_bf16_f32 v58, v71, v73
	v_cvt_pk_bf16_f32 v59, v75, v79
	global_store_dwordx4 v[60:61], v[56:59], off sc1
	s_waitcnt lgkmcnt(0)

.LBB0_31:
	s_andn2_b64 vcc, exec, s[8:9]
	s_cbranch_vccnz .LBB0_33
	s_lshl_b64 s[8:9], s[4:5], 22
	s_add_u32 s10, s90, s8
	s_addc_u32 s11, s91, s9
	s_lshl_b64 s[8:9], s[4:5], 21
	s_add_u32 s5, s34, s8
	s_addc_u32 s12, s35, s9
	s_lshl_b32 s4, s4, 9
	s_sub_i32 s4, s38, s4
	s_and_b32 s8, s4, 0x3c0
	s_and_b32 s4, s36, 0x3c0
	s_xor_b32 s13, s8, 0x200
	v_bitop3_b32 v2, s8, v1, v54 bitop3:0xde
	s_lshl_b32 s8, s4, 2
	s_add_u32 s8, s10, s8
	s_addc_u32 s9, s11, 0
	v_mov_b32_e32 v9, v3
	v_lshl_add_u64 v[56:57], s[8:9], 0, v[8:9]
	v_lshlrev_b32_e32 v2, 12, v2
	v_lshl_add_u64 v[116:117], v[56:57], 0, v[2:3]
	v_add_co_u32_e32 v60, vcc, s40, v116
	s_lshl_b32 s8, s13, 1
	s_nop 0
	v_addc_co_u32_e32 v61, vcc, 0, v117, vcc
	v_add_co_u32_e32 v64, vcc, s41, v116
	global_load_dwordx4 v[56:59], v[116:117], off
	s_nop 0
	global_load_dwordx4 v[60:63], v[60:61], off
	v_addc_co_u32_e32 v65, vcc, 0, v117, vcc
	v_add_co_u32_e32 v68, vcc, s42, v116
	s_add_u32 s8, s5, s8
	s_nop 0
	v_addc_co_u32_e32 v69, vcc, 0, v117, vcc
	v_add_co_u32_e32 v72, vcc, s43, v116
	global_load_dwordx4 v[64:67], v[64:65], off
	s_nop 0
	global_load_dwordx4 v[68:71], v[68:69], off
	v_addc_co_u32_e32 v73, vcc, 0, v117, vcc
	v_add_co_u32_e32 v76, vcc, s44, v116
	s_addc_u32 s9, s12, 0
	s_nop 0
	v_addc_co_u32_e32 v77, vcc, 0, v117, vcc
	v_add_co_u32_e32 v80, vcc, s45, v116
	global_load_dwordx4 v[72:75], v[72:73], off
	s_nop 0
	global_load_dwordx4 v[76:79], v[76:77], off
	v_addc_co_u32_e32 v81, vcc, 0, v117, vcc
	v_add_co_u32_e32 v84, vcc, s52, v116
	v_mov_b32_e32 v11, v3
	s_nop 0
	v_addc_co_u32_e32 v85, vcc, 0, v117, vcc
	v_add_co_u32_e32 v88, vcc, s53, v116
	global_load_dwordx4 v[80:83], v[80:81], off
	s_nop 0
	global_load_dwordx4 v[84:87], v[84:85], off
	v_addc_co_u32_e32 v89, vcc, 0, v117, vcc
	v_add_co_u32_e32 v92, vcc, s54, v116
	v_or_b32_e32 v2, s4, v13
	s_nop 0
	v_addc_co_u32_e32 v93, vcc, 0, v117, vcc
	v_add_co_u32_e32 v96, vcc, s55, v116
	global_load_dwordx4 v[88:91], v[88:89], off
	s_nop 0
	global_load_dwordx4 v[92:95], v[92:93], off
	v_addc_co_u32_e32 v97, vcc, 0, v117, vcc
	v_add_co_u32_e32 v100, vcc, s60, v116
	v_lshlrev_b32_e32 v2, 11, v2
	s_nop 0
	v_addc_co_u32_e32 v101, vcc, 0, v117, vcc
	v_add_co_u32_e32 v104, vcc, s61, v116
	global_load_dwordx4 v[96:99], v[96:97], off
	s_nop 0
	global_load_dwordx4 v[100:103], v[100:101], off
	v_addc_co_u32_e32 v105, vcc, 0, v117, vcc
	v_add_co_u32_e32 v108, vcc, s62, v116
	s_nop 1
	v_addc_co_u32_e32 v109, vcc, 0, v117, vcc
	global_load_dwordx4 v[104:107], v[104:105], off
	s_nop 0
	global_load_dwordx4 v[108:111], v[108:109], off
	v_add_co_u32_e32 v112, vcc, s63, v116
	s_nop 1
	v_addc_co_u32_e32 v113, vcc, 0, v117, vcc
	global_load_dwordx4 v[112:115], v[112:113], off
	v_add_co_u32_e32 v116, vcc, s65, v116
	s_nop 1
	v_addc_co_u32_e32 v117, vcc, 0, v117, vcc
	global_load_dwordx4 v[116:119], v[116:117], off
	s_waitcnt vmcnt(15)
	ds_write2_b32 v12, v56, v57 offset1:1
	ds_write2_b32 v12, v58, v59 offset0:2 offset1:3
	s_waitcnt vmcnt(14)
	ds_write2_b32 v22, v60, v61 offset1:1
	ds_write2_b32 v23, v62, v63 offset1:1
	s_waitcnt vmcnt(13)
	ds_write2_b32 v24, v64, v65 offset1:1
	ds_write2_b32 v25, v66, v67 offset1:1
	s_waitcnt vmcnt(12)
	ds_write2_b32 v26, v68, v69 offset1:1
	ds_write2_b32 v27, v70, v71 offset1:1
	s_waitcnt vmcnt(11)
	ds_write2_b32 v28, v72, v73 offset1:1
	ds_write2_b32 v29, v74, v75 offset1:1
	s_waitcnt vmcnt(10)
	ds_write2_b32 v30, v76, v77 offset1:1
	ds_write2_b32 v31, v78, v79 offset1:1
	s_waitcnt vmcnt(9)
	ds_write2_b32 v32, v80, v81 offset1:1
	ds_write2_b32 v33, v82, v83 offset1:1
	s_waitcnt vmcnt(8)
	ds_write2_b32 v34, v84, v85 offset1:1
	ds_write2_b32 v35, v86, v87 offset1:1
	s_waitcnt vmcnt(7)
	ds_write2_b32 v36, v88, v89 offset1:1
	ds_write2_b32 v37, v90, v91 offset1:1
	s_waitcnt vmcnt(6)
	ds_write2_b32 v38, v92, v93 offset1:1
	ds_write2_b32 v39, v94, v95 offset1:1
	s_waitcnt vmcnt(5)
	ds_write2_b32 v40, v96, v97 offset1:1
	ds_write2_b32 v41, v98, v99 offset1:1
	s_waitcnt vmcnt(4)
	ds_write2_b32 v42, v100, v101 offset1:1
	ds_write2_b32 v43, v102, v103 offset1:1
	s_waitcnt vmcnt(3)
	ds_write2_b32 v44, v104, v105 offset1:1
	ds_write2_b32 v45, v106, v107 offset1:1
	s_waitcnt vmcnt(2)
	ds_write2_b32 v46, v108, v109 offset1:1
	ds_write2_b32 v47, v110, v111 offset1:1
	s_waitcnt vmcnt(1)
	ds_write2_b32 v48, v112, v113 offset1:1
	ds_write2_b32 v49, v114, v115 offset1:1
	s_waitcnt vmcnt(0)
	ds_write2_b32 v51, v116, v117 offset1:1
	ds_write2_b32 v52, v118, v119 offset1:1
	s_waitcnt lgkmcnt(0)
	ds_read2_b32 v[60:61], v14 offset0:65 offset1:73
	ds_read2_b32 v[62:63], v14 offset1:8
	ds_read2_b32 v[64:65], v14 offset0:130 offset1:138
	ds_read2_b32 v[66:67], v14 offset0:195 offset1:203
	ds_read2_b32 v[68:69], v53 offset0:4 offset1:12
	ds_read2_b32 v[70:71], v53 offset0:69 offset1:77
	ds_read2_b32 v[72:73], v53 offset0:134 offset1:142
	ds_read2_b32 v[74:75], v53 offset0:199 offset1:207
	v_lshl_add_u64 v[76:77], s[8:9], 0, v[10:11]
	s_waitcnt lgkmcnt(6)
	v_cvt_pk_bf16_f32 v56, v62, v60
	s_waitcnt lgkmcnt(4)
	v_cvt_pk_bf16_f32 v57, v64, v66
	s_waitcnt lgkmcnt(2)
	v_cvt_pk_bf16_f32 v58, v68, v70
	s_waitcnt lgkmcnt(0)
	v_cvt_pk_bf16_f32 v59, v72, v74
	v_lshl_add_u64 v[78:79], v[76:77], 0, v[2:3]
	global_store_dwordx4 v[78:79], v[56:59], off sc1
	v_or_b32_e32 v2, s4, v15
	v_lshlrev_b32_e32 v2, 11, v2
	v_cvt_pk_bf16_f32 v56, v63, v61
	v_cvt_pk_bf16_f32 v57, v65, v67
	v_cvt_pk_bf16_f32 v58, v69, v71
	v_cvt_pk_bf16_f32 v59, v73, v75
	ds_read2_b32 v[62:63], v14 offset0:81 offset1:89
	ds_read2_b32 v[64:65], v14 offset0:16 offset1:24
	ds_read2_b32 v[66:67], v14 offset0:146 offset1:154
	ds_read2_b32 v[68:69], v14 offset0:211 offset1:219
	ds_read2_b32 v[70:71], v53 offset0:20 offset1:28
	ds_read2_b32 v[72:73], v53 offset0:85 offset1:93
	ds_read2_b32 v[74:75], v53 offset0:150 offset1:158
	ds_read2_b32 v[78:79], v53 offset0:215 offset1:223
	v_lshl_add_u64 v[60:61], v[76:77], 0, v[2:3]
	v_or_b32_e32 v2, s4, v16
	v_lshlrev_b32_e32 v2, 11, v2
	global_store_dwordx4 v[60:61], v[56:59], off sc1
	v_lshl_add_u64 v[60:61], v[76:77], 0, v[2:3]
	v_or_b32_e32 v2, s4, v17
	s_waitcnt lgkmcnt(6)
	v_cvt_pk_bf16_f32 v56, v64, v62
	s_waitcnt lgkmcnt(4)
	v_cvt_pk_bf16_f32 v57, v66, v68
	s_waitcnt lgkmcnt(2)
	v_cvt_pk_bf16_f32 v58, v70, v72
	s_waitcnt lgkmcnt(0)
	v_cvt_pk_bf16_f32 v59, v74, v78
	global_store_dwordx4 v[60:61], v[56:59], off sc1
	v_lshlrev_b32_e32 v2, 11, v2
	v_lshl_add_u64 v[60:61], v[76:77], 0, v[2:3]
	v_cvt_pk_bf16_f32 v56, v65, v63
	v_cvt_pk_bf16_f32 v57, v67, v69
	v_cvt_pk_bf16_f32 v58, v71, v73
	v_cvt_pk_bf16_f32 v59, v75, v79
	ds_read2_b32 v[62:63], v14 offset0:32 offset1:40
	ds_read2_b32 v[64:65], v14 offset0:97 offset1:105
	ds_read2_b32 v[66:67], v14 offset0:162 offset1:170
	ds_read2_b32 v[68:69], v14 offset0:227 offset1:235
	ds_read2_b32 v[70:71], v53 offset0:36 offset1:44
	ds_read2_b32 v[72:73], v53 offset0:101 offset1:109
	ds_read2_b32 v[74:75], v53 offset0:166 offset1:174
	ds_read2_b32 v[78:79], v53 offset0:231 offset1:239
	v_or_b32_e32 v2, s4, v18
	v_lshlrev_b32_e32 v2, 11, v2
	global_store_dwordx4 v[60:61], v[56:59], off sc1
	v_lshl_add_u64 v[60:61], v[76:77], 0, v[2:3]
	v_or_b32_e32 v2, s4, v19
	s_waitcnt lgkmcnt(6)
	v_cvt_pk_bf16_f32 v56, v62, v64
	s_waitcnt lgkmcnt(4)
	v_cvt_pk_bf16_f32 v57, v66, v68
	s_waitcnt lgkmcnt(2)
	v_cvt_pk_bf16_f32 v58, v70, v72
	s_waitcnt lgkmcnt(0)
	v_cvt_pk_bf16_f32 v59, v74, v78
	global_store_dwordx4 v[60:61], v[56:59], off sc1
	v_lshlrev_b32_e32 v2, 11, v2
	v_lshl_add_u64 v[60:61], v[76:77], 0, v[2:3]
	v_cvt_pk_bf16_f32 v56, v63, v65
	v_cvt_pk_bf16_f32 v57, v67, v69
	v_cvt_pk_bf16_f32 v58, v71, v73
	v_cvt_pk_bf16_f32 v59, v75, v79
	ds_read2_b32 v[62:63], v14 offset0:48 offset1:56
	ds_read2_b32 v[64:65], v14 offset0:113 offset1:121
	ds_read2_b32 v[66:67], v14 offset0:178 offset1:186
	ds_read2_b32 v[68:69], v14 offset0:243 offset1:251
	ds_read2_b32 v[70:71], v53 offset0:52 offset1:60
	ds_read2_b32 v[72:73], v53 offset0:117 offset1:125
	ds_read2_b32 v[74:75], v53 offset0:182 offset1:190
	ds_read2_b32 v[78:79], v53 offset0:247 offset1:255
	v_or_b32_e32 v2, s4, v20
	v_lshlrev_b32_e32 v2, 11, v2
	global_store_dwordx4 v[60:61], v[56:59], off sc1
	v_lshl_add_u64 v[60:61], v[76:77], 0, v[2:3]
	v_or_b32_e32 v2, s4, v21
	s_waitcnt lgkmcnt(6)
	v_cvt_pk_bf16_f32 v56, v62, v64
	s_waitcnt lgkmcnt(4)
	v_cvt_pk_bf16_f32 v57, v66, v68
	s_waitcnt lgkmcnt(2)
	v_cvt_pk_bf16_f32 v58, v70, v72
	s_waitcnt lgkmcnt(0)
	v_cvt_pk_bf16_f32 v59, v74, v78
	v_lshlrev_b32_e32 v2, 11, v2
	global_store_dwordx4 v[60:61], v[56:59], off sc1
	v_lshl_add_u64 v[60:61], v[76:77], 0, v[2:3]
	s_nop 0
	v_cvt_pk_bf16_f32 v56, v63, v65
	v_cvt_pk_bf16_f32 v57, v67, v69
	v_cvt_pk_bf16_f32 v58, v71, v73
	v_cvt_pk_bf16_f32 v59, v75, v79
	global_store_dwordx4 v[60:61], v[56:59], off sc1
	s_waitcnt lgkmcnt(0)

.LBB0_34:
	s_andn2_b64 vcc, exec, s[8:9]
	s_cbranch_vccnz .LBB0_23
	s_cmpk_lt_i32 s14, 0xa80
	s_cbranch_scc1 .LBB0_23
	s_mul_i32 s4, s0, 0xaaab
	s_lshr_b32 s5, s4, 20
	s_mul_i32 s5, s5, 24
	s_sub_i32 s0, s0, s5
	s_lshr_b32 s4, s4, 14
	s_lshl_b32 s0, s0, 6
	s_and_b32 s5, s4, 0xffc0
	s_and_b32 s4, s0, 0xffc0
	v_or_b32_e32 v2, s5, v1
	s_lshl_b32 s0, s4, 2
	v_lshl_add_u64 v[56:57], v[4:5], 0, s[0:1]
	v_mul_u32_u24_e32 v2, 0x1800, v2
	v_lshl_add_u64 v[116:117], v[56:57], 0, v[2:3]
	v_add_co_u32_e32 v64, vcc, s42, v116
	s_movk_i32 s0, 0x6000
	s_nop 0
	v_addc_co_u32_e32 v65, vcc, 0, v117, vcc
	v_add_co_u32_e32 v60, vcc, s0, v116
	s_mov_b32 s0, 0x12000
	s_nop 0
	v_addc_co_u32_e32 v61, vcc, 0, v117, vcc
	v_add_co_u32_e32 v68, vcc, s0, v116
	s_mov_b32 s0, 0x1e000
	s_nop 0
	v_addc_co_u32_e32 v69, vcc, 0, v117, vcc
	v_add_co_u32_e32 v72, vcc, s45, v116
	global_load_dwordx4 v[56:59], v[116:117], off
	s_nop 0
	global_load_dwordx4 v[60:63], v[60:61], off
	v_addc_co_u32_e32 v73, vcc, 0, v117, vcc
	v_add_co_u32_e32 v80, vcc, s54, v116
	global_load_dwordx4 v[64:67], v[64:65], off
	s_nop 0
	global_load_dwordx4 v[68:71], v[68:69], off
	v_addc_co_u32_e32 v81, vcc, 0, v117, vcc
	v_add_co_u32_e32 v88, vcc, s61, v116
	v_or_b32_e32 v2, s4, v13
	s_nop 0
	v_addc_co_u32_e32 v89, vcc, 0, v117, vcc
	v_add_co_u32_e32 v96, vcc, s65, v116
	v_lshlrev_b32_e32 v2, 11, v2
	s_nop 0
	v_addc_co_u32_e32 v97, vcc, 0, v117, vcc
	v_add_co_u32_e32 v76, vcc, s0, v116
	s_mov_b32 s0, 0x2a000
	s_nop 0
	v_addc_co_u32_e32 v77, vcc, 0, v117, vcc
	v_add_co_u32_e32 v84, vcc, s0, v116
	s_mov_b32 s0, 0x36000
	s_nop 0
	v_addc_co_u32_e32 v85, vcc, 0, v117, vcc
	v_add_co_u32_e32 v92, vcc, s0, v116
	s_mov_b32 s0, 0x42000
	s_nop 0
	v_addc_co_u32_e32 v93, vcc, 0, v117, vcc
	v_add_co_u32_e32 v100, vcc, s0, v116
	global_load_dwordx4 v[72:75], v[72:73], off
	s_nop 0
	global_load_dwordx4 v[76:79], v[76:77], off
	v_addc_co_u32_e32 v101, vcc, 0, v117, vcc
	v_add_co_u32_e32 v104, vcc, s66, v116
	global_load_dwordx4 v[80:83], v[80:81], off
	s_nop 0
	global_load_dwordx4 v[84:87], v[84:85], off
	v_addc_co_u32_e32 v105, vcc, 0, v117, vcc
	v_add_co_u32_e32 v108, vcc, s67, v116
	global_load_dwordx4 v[88:91], v[88:89], off
	s_nop 0
	global_load_dwordx4 v[92:95], v[92:93], off
	v_addc_co_u32_e32 v109, vcc, 0, v117, vcc
	global_load_dwordx4 v[96:99], v[96:97], off
	s_nop 0
	global_load_dwordx4 v[100:103], v[100:101], off
	s_nop 0
	global_load_dwordx4 v[104:107], v[104:105], off
	s_nop 0
	global_load_dwordx4 v[108:111], v[108:109], off
	v_add_co_u32_e32 v112, vcc, s68, v116
	s_lshl_b32 s0, s5, 1
	s_nop 0
	v_addc_co_u32_e32 v113, vcc, 0, v117, vcc
	global_load_dwordx4 v[112:115], v[112:113], off
	v_add_co_u32_e32 v116, vcc, s69, v116
	s_nop 1
	v_addc_co_u32_e32 v117, vcc, 0, v117, vcc
	global_load_dwordx4 v[116:119], v[116:117], off
	s_waitcnt vmcnt(15)
	ds_write2_b32 v12, v56, v57 offset1:1
	ds_write2_b32 v12, v58, v59 offset0:2 offset1:3
	s_waitcnt vmcnt(13)
	ds_write2_b32 v24, v64, v65 offset1:1
	ds_write2_b32 v25, v66, v67 offset1:1
	ds_write2_b32 v22, v60, v61 offset1:1
	ds_write2_b32 v23, v62, v63 offset1:1
	s_waitcnt vmcnt(12)
	ds_write2_b32 v26, v68, v69 offset1:1
	ds_write2_b32 v27, v70, v71 offset1:1
	s_waitcnt vmcnt(11)
	ds_write2_b32 v28, v72, v73 offset1:1
	ds_write2_b32 v29, v74, v75 offset1:1
	s_waitcnt vmcnt(10)
	ds_write2_b32 v30, v76, v77 offset1:1
	ds_write2_b32 v31, v78, v79 offset1:1
	s_waitcnt vmcnt(9)
	ds_write2_b32 v32, v80, v81 offset1:1
	ds_write2_b32 v33, v82, v83 offset1:1
	s_waitcnt vmcnt(8)
	ds_write2_b32 v34, v84, v85 offset1:1
	ds_write2_b32 v35, v86, v87 offset1:1
	s_waitcnt vmcnt(7)
	ds_write2_b32 v36, v88, v89 offset1:1
	ds_write2_b32 v37, v90, v91 offset1:1
	s_waitcnt vmcnt(6)
	ds_write2_b32 v38, v92, v93 offset1:1
	ds_write2_b32 v39, v94, v95 offset1:1
	s_waitcnt vmcnt(5)
	ds_write2_b32 v40, v96, v97 offset1:1
	ds_write2_b32 v41, v98, v99 offset1:1
	s_waitcnt vmcnt(4)
	ds_write2_b32 v42, v100, v101 offset1:1
	ds_write2_b32 v43, v102, v103 offset1:1
	s_waitcnt vmcnt(3)
	ds_write2_b32 v44, v104, v105 offset1:1
	ds_write2_b32 v45, v106, v107 offset1:1
	s_waitcnt vmcnt(2)
	ds_write2_b32 v46, v108, v109 offset1:1
	ds_write2_b32 v47, v110, v111 offset1:1
	s_waitcnt vmcnt(1)
	ds_write2_b32 v48, v112, v113 offset1:1
	ds_write2_b32 v49, v114, v115 offset1:1
	s_waitcnt vmcnt(0)
	ds_write2_b32 v51, v116, v117 offset1:1
	ds_write2_b32 v52, v118, v119 offset1:1
	s_waitcnt lgkmcnt(0)
	ds_read2_b32 v[60:61], v14 offset0:65 offset1:73
	ds_read2_b32 v[62:63], v14 offset1:8
	ds_read2_b32 v[64:65], v14 offset0:130 offset1:138
	ds_read2_b32 v[66:67], v14 offset0:195 offset1:203
	ds_read2_b32 v[68:69], v53 offset0:4 offset1:12
	ds_read2_b32 v[70:71], v53 offset0:69 offset1:77
	ds_read2_b32 v[72:73], v53 offset0:134 offset1:142
	ds_read2_b32 v[74:75], v53 offset0:199 offset1:207
	v_lshl_add_u64 v[76:77], v[6:7], 0, s[0:1]
	s_waitcnt lgkmcnt(6)
	v_cvt_pk_bf16_f32 v56, v62, v60
	s_waitcnt lgkmcnt(4)
	v_cvt_pk_bf16_f32 v57, v64, v66
	s_waitcnt lgkmcnt(2)
	v_cvt_pk_bf16_f32 v58, v68, v70
	s_waitcnt lgkmcnt(0)
	v_cvt_pk_bf16_f32 v59, v72, v74
	v_lshl_add_u64 v[78:79], v[76:77], 0, v[2:3]
	global_store_dwordx4 v[78:79], v[56:59], off sc1
	v_or_b32_e32 v2, s4, v15
	v_lshlrev_b32_e32 v2, 11, v2
	v_cvt_pk_bf16_f32 v56, v63, v61
	v_cvt_pk_bf16_f32 v57, v65, v67
	v_cvt_pk_bf16_f32 v58, v69, v71
	v_cvt_pk_bf16_f32 v59, v73, v75
	ds_read2_b32 v[62:63], v14 offset0:81 offset1:89
	ds_read2_b32 v[64:65], v14 offset0:16 offset1:24
	ds_read2_b32 v[66:67], v14 offset0:146 offset1:154
	ds_read2_b32 v[68:69], v14 offset0:211 offset1:219
	ds_read2_b32 v[70:71], v53 offset0:20 offset1:28
	ds_read2_b32 v[72:73], v53 offset0:85 offset1:93
	ds_read2_b32 v[74:75], v53 offset0:150 offset1:158
	ds_read2_b32 v[78:79], v53 offset0:215 offset1:223
	v_lshl_add_u64 v[60:61], v[76:77], 0, v[2:3]
	v_or_b32_e32 v2, s4, v16
	v_lshlrev_b32_e32 v2, 11, v2
	global_store_dwordx4 v[60:61], v[56:59], off sc1
	v_lshl_add_u64 v[60:61], v[76:77], 0, v[2:3]
	v_or_b32_e32 v2, s4, v17
	s_waitcnt lgkmcnt(6)
	v_cvt_pk_bf16_f32 v56, v64, v62
	s_waitcnt lgkmcnt(4)
	v_cvt_pk_bf16_f32 v57, v66, v68
	s_waitcnt lgkmcnt(2)
	v_cvt_pk_bf16_f32 v58, v70, v72
	s_waitcnt lgkmcnt(0)
	v_cvt_pk_bf16_f32 v59, v74, v78
	global_store_dwordx4 v[60:61], v[56:59], off sc1
	v_lshlrev_b32_e32 v2, 11, v2
	v_lshl_add_u64 v[60:61], v[76:77], 0, v[2:3]
	v_cvt_pk_bf16_f32 v56, v65, v63
	v_cvt_pk_bf16_f32 v57, v67, v69
	v_cvt_pk_bf16_f32 v58, v71, v73
	v_cvt_pk_bf16_f32 v59, v75, v79
	ds_read2_b32 v[62:63], v14 offset0:32 offset1:40
	ds_read2_b32 v[64:65], v14 offset0:97 offset1:105
	ds_read2_b32 v[66:67], v14 offset0:162 offset1:170
	ds_read2_b32 v[68:69], v14 offset0:227 offset1:235
	ds_read2_b32 v[70:71], v53 offset0:36 offset1:44
	ds_read2_b32 v[72:73], v53 offset0:101 offset1:109
	ds_read2_b32 v[74:75], v53 offset0:166 offset1:174
	ds_read2_b32 v[78:79], v53 offset0:231 offset1:239
	v_or_b32_e32 v2, s4, v18
	v_lshlrev_b32_e32 v2, 11, v2
	global_store_dwordx4 v[60:61], v[56:59], off sc1
	v_lshl_add_u64 v[60:61], v[76:77], 0, v[2:3]
	v_or_b32_e32 v2, s4, v19
	s_waitcnt lgkmcnt(6)
	v_cvt_pk_bf16_f32 v56, v62, v64
	s_waitcnt lgkmcnt(4)
	v_cvt_pk_bf16_f32 v57, v66, v68
	s_waitcnt lgkmcnt(2)
	v_cvt_pk_bf16_f32 v58, v70, v72
	s_waitcnt lgkmcnt(0)
	v_cvt_pk_bf16_f32 v59, v74, v78
	global_store_dwordx4 v[60:61], v[56:59], off sc1
	v_lshlrev_b32_e32 v2, 11, v2
	v_lshl_add_u64 v[60:61], v[76:77], 0, v[2:3]
	v_cvt_pk_bf16_f32 v56, v63, v65
	v_cvt_pk_bf16_f32 v57, v67, v69
	v_cvt_pk_bf16_f32 v58, v71, v73
	v_cvt_pk_bf16_f32 v59, v75, v79
	ds_read2_b32 v[62:63], v14 offset0:48 offset1:56
	ds_read2_b32 v[64:65], v14 offset0:113 offset1:121
	ds_read2_b32 v[66:67], v14 offset0:178 offset1:186
	ds_read2_b32 v[68:69], v14 offset0:243 offset1:251
	ds_read2_b32 v[70:71], v53 offset0:52 offset1:60
	ds_read2_b32 v[72:73], v53 offset0:117 offset1:125
	ds_read2_b32 v[74:75], v53 offset0:182 offset1:190
	ds_read2_b32 v[78:79], v53 offset0:247 offset1:255
	v_or_b32_e32 v2, s4, v20
	v_lshlrev_b32_e32 v2, 11, v2
	global_store_dwordx4 v[60:61], v[56:59], off sc1
	v_lshl_add_u64 v[60:61], v[76:77], 0, v[2:3]
	v_or_b32_e32 v2, s4, v21
	s_waitcnt lgkmcnt(6)
	v_cvt_pk_bf16_f32 v56, v62, v64
	s_waitcnt lgkmcnt(4)
	v_cvt_pk_bf16_f32 v57, v66, v68
	s_waitcnt lgkmcnt(2)
	v_cvt_pk_bf16_f32 v58, v70, v72
	s_waitcnt lgkmcnt(0)
	v_cvt_pk_bf16_f32 v59, v74, v78
	v_lshlrev_b32_e32 v2, 11, v2
	global_store_dwordx4 v[60:61], v[56:59], off sc1
	v_lshl_add_u64 v[60:61], v[76:77], 0, v[2:3]
	s_nop 0
	v_cvt_pk_bf16_f32 v56, v63, v65
	v_cvt_pk_bf16_f32 v57, v67, v69
	v_cvt_pk_bf16_f32 v58, v71, v73
	v_cvt_pk_bf16_f32 v59, v75, v79
	global_store_dwordx4 v[60:61], v[56:59], off sc1
	s_waitcnt lgkmcnt(0)
	s_branch .LBB0_23

.LBB0_54:
	v_ashrrev_i32_e32 v9, 6, v2
	v_mul_lo_u32 v9, v9, v6
	v_cvt_f32_i32_e32 v9, v9
	v_add_u32_e32 v2, s50, v2
	v_cmp_lt_i32_e32 vcc, s12, v2
	s_or_b64 s[8:9], vcc, s[8:9]
	v_mul_f32_e32 v9, 0x39800000, v9
	v_mul_f32_e64 v11, |v9|, 0.5
	v_fract_f32_e32 v13, v11
	v_add_f32_e32 v13, v13, v13
	v_cmp_neq_f32_e32 vcc, s10, v11
	v_cmp_gt_f32_e64 s[14:15], |v9|, 1.0
	v_and_b32_e32 v10, 0x7fffffff, v9
	v_cndmask_b32_e32 v11, 0, v13, vcc
	v_cndmask_b32_e64 v11, |v9|, v11, s[14:15]
	v_add_f32_e32 v13, v11, v11
	v_rndne_f32_e32 v13, v13
	v_fmac_f32_e32 v11, -0.5, v13
	v_cvt_i32_f32_e32 v13, v13
	v_mul_f32_e32 v14, v11, v11
	v_fmamk_f32 v15, v14, 0x3e75aa41, v3
	v_fmamk_f32 v17, v14, 0x3d4be544, v7
	v_fmaak_f32 v15, v14, v15, 0x40234736
	v_fmaak_f32 v17, v14, v17, 0xbfaad1da
	v_mul_f32_e32 v16, v11, v14
	v_fmaak_f32 v15, v14, v15, 0xc0a55e0e
	v_fmaak_f32 v17, v14, v17, 0x4081e0d3
	v_and_b32_e32 v18, 2, v13
	v_and_b32_e32 v19, 1, v13
	v_lshlrev_b32_e32 v13, 30, v13
	v_mul_f32_e32 v15, v16, v15
	v_fmaak_f32 v16, v14, v17, 0xc09de9e6
	v_xor_b32_e32 v10, v10, v9
	v_and_b32_e32 v13, 0x80000000, v13
	v_fmac_f32_e32 v15, 0x40490fdb, v11
	v_fma_f32 v11, v14, v16, 1.0
	v_cmp_eq_u32_e32 vcc, 0, v19
	v_xor_b32_e32 v10, v10, v13
	s_nop 0
	v_cndmask_b32_e64 v13, -v15, v11, vcc
	v_cndmask_b32_e32 v11, v11, v15, vcc
	v_cmp_eq_u32_e32 vcc, 0, v18
	v_xor_b32_e32 v10, v10, v11
	s_nop 0
	v_cndmask_b32_e64 v13, -v13, v13, vcc
	v_mul_f32_e32 v11, 0x3c3504f3, v13
	v_mul_f32_e32 v13, 0x3c3504f3, v10
	v_cmp_class_f32_e64 vcc, v9, s11
	s_nop 1
	v_cndmask_b32_e32 v10, v8, v11, vcc
	v_cndmask_b32_e32 v11, v8, v13, vcc
	global_store_dwordx2 v[4:5], v[10:11], off sc1
	v_lshl_add_u64 v[4:5], v[4:5], 0, s[4:5]
	s_andn2_b64 exec, exec, s[8:9]
	s_cbranch_execnz .LBB0_54

.LBB0_57:
	v_ashrrev_i32_e32 v9, 6, v2
	v_mul_lo_u32 v9, v9, v6
	v_cvt_f32_i32_e32 v9, v9
	v_add_u32_e32 v2, s50, v2
	v_cmp_lt_i32_e32 vcc, s12, v2
	s_or_b64 s[8:9], vcc, s[8:9]
	v_mul_f32_e32 v9, 0x3a000000, v9
	v_mul_f32_e64 v11, |v9|, 0.5
	v_fract_f32_e32 v13, v11
	v_add_f32_e32 v13, v13, v13
	v_cmp_neq_f32_e32 vcc, s10, v11
	v_cmp_gt_f32_e64 s[14:15], |v9|, 1.0
	v_and_b32_e32 v10, 0x7fffffff, v9
	v_cndmask_b32_e32 v11, 0, v13, vcc
	v_cndmask_b32_e64 v11, |v9|, v11, s[14:15]
	v_add_f32_e32 v13, v11, v11
	v_rndne_f32_e32 v13, v13
	v_fmac_f32_e32 v11, -0.5, v13
	v_cvt_i32_f32_e32 v13, v13
	v_mul_f32_e32 v14, v11, v11
	v_fmamk_f32 v15, v14, 0x3e75aa41, v3
	v_fmamk_f32 v17, v14, 0x3d4be544, v7
	v_fmaak_f32 v15, v14, v15, 0x40234736
	v_fmaak_f32 v17, v14, v17, 0xbfaad1da
	v_mul_f32_e32 v16, v11, v14
	v_fmaak_f32 v15, v14, v15, 0xc0a55e0e
	v_fmaak_f32 v17, v14, v17, 0x4081e0d3
	v_and_b32_e32 v18, 2, v13
	v_and_b32_e32 v19, 1, v13
	v_lshlrev_b32_e32 v13, 30, v13
	v_mul_f32_e32 v15, v16, v15
	v_fmaak_f32 v16, v14, v17, 0xc09de9e6
	v_xor_b32_e32 v10, v10, v9
	v_and_b32_e32 v13, 0x80000000, v13
	v_fmac_f32_e32 v15, 0x40490fdb, v11
	v_fma_f32 v11, v14, v16, 1.0
	v_cmp_eq_u32_e32 vcc, 0, v19
	v_xor_b32_e32 v10, v10, v13
	s_nop 0
	v_cndmask_b32_e64 v13, -v15, v11, vcc
	v_cndmask_b32_e32 v11, v11, v15, vcc
	v_cmp_eq_u32_e32 vcc, 0, v18
	v_xor_b32_e32 v10, v10, v11
	s_nop 0
	v_cndmask_b32_e64 v13, -v13, v13, vcc
	v_mul_f32_e32 v11, 0x3c800000, v13
	v_mul_f32_e32 v13, 0x3c800000, v10
	v_cmp_class_f32_e64 vcc, v9, s11
	s_nop 1
	v_cndmask_b32_e32 v10, v8, v11, vcc
	v_cndmask_b32_e32 v11, v8, v13, vcc
	global_store_dwordx2 v[4:5], v[10:11], off sc1
	v_lshl_add_u64 v[4:5], v[4:5], 0, s[4:5]
	s_andn2_b64 exec, exec, s[8:9]
	s_cbranch_execnz .LBB0_57

.LBB0_142:
	s_add_i32 s14, s16, 0xffffbfff
	s_add_u32 s19, s16, -1
	v_readlane_b32 s48, v252, 3
	s_addc_u32 s15, s17, -1
	v_readlane_b32 s50, v252, 5
	v_readlane_b32 s51, v252, 6
	v_readlane_b32 s52, v252, 7
	v_readlane_b32 s53, v252, 8
	v_readlane_b32 s54, v252, 9
	v_readlane_b32 s55, v252, 10
	s_cmpk_lt_i32 s6, 0x4000
	v_readlane_b32 s49, v252, 4
	s_mov_b64 s[54:55], s[50:51]
	s_cselect_b32 s15, s15, 0
	s_cselect_b32 s14, s19, s14
	s_mov_b64 s[52:53], s[48:49]
	s_cselect_b32 s19, s53, s55
	s_cselect_b32 s22, s52, s54
	s_lshl_b64 s[14:15], s[14:15], 12
	s_add_u32 s14, s22, s14
	s_addc_u32 s15, s19, s15
	global_load_dwordx4 v[68:71], v66, s[14:15]
	global_load_dwordx4 v[72:75], v66, s[14:15] offset:1024
	global_load_dwordx4 v[76:79], v66, s[14:15] offset:2048
	global_load_dwordx4 v[80:83], v66, s[14:15] offset:3072
	s_add_i32 s14, s16, 0xffffc000
	s_cmpk_lt_i32 s16, 0x4000
	s_cselect_b32 s15, s17, 0
	s_cselect_b32 s14, s16, s14
	s_cselect_b32 s19, s53, s55
	s_cselect_b32 s22, s52, s54
	s_lshl_b64 s[14:15], s[14:15], 12
	s_add_u32 s14, s22, s14
	s_addc_u32 s15, s19, s15
	global_load_dwordx4 v[46:49], v66, s[14:15]
	global_load_dwordx4 v[42:45], v66, s[14:15] offset:1024
	global_load_dwordx4 v[38:41], v66, s[14:15] offset:2048
	global_load_dwordx4 v[34:37], v66, s[14:15] offset:3072
	s_add_u32 s14, s16, 1
	s_addc_u32 s15, s17, 0
	s_add_i32 s19, s16, 0xffffc001
	s_cmpk_lt_i32 s14, 0x4000
	s_cselect_b32 s15, s15, 0
	s_cselect_b32 s14, s14, s19
	s_cselect_b32 s19, s53, s55
	s_cselect_b32 s22, s52, s54
	s_lshl_b64 s[14:15], s[14:15], 12
	s_add_u32 s14, s22, s14
	s_addc_u32 s15, s19, s15
	global_load_dwordx4 v[30:33], v66, s[14:15]
	global_load_dwordx4 v[26:29], v66, s[14:15] offset:1024
	global_load_dwordx4 v[22:25], v66, s[14:15] offset:2048
	global_load_dwordx4 v[18:21], v66, s[14:15] offset:3072
	s_add_u32 s14, s16, 2
	s_addc_u32 s15, s17, 0
	s_add_i32 s19, s16, 0xffffc002
	s_cmpk_lt_i32 s14, 0x4000
	s_cselect_b32 s15, s15, 0
	s_cselect_b32 s14, s14, s19
	s_cselect_b32 s19, s53, s55
	s_cselect_b32 s22, s52, s54
	s_lshl_b64 s[14:15], s[14:15], 12
	s_add_u32 s14, s22, s14
	s_addc_u32 s15, s19, s15
	s_waitcnt lgkmcnt(0)
	global_load_dwordx4 v[14:17], v66, s[14:15]
	global_load_dwordx4 v[10:13], v66, s[14:15] offset:1024
	global_load_dwordx4 v[6:9], v66, s[14:15] offset:2048
	global_load_dwordx4 v[2:5], v66, s[14:15] offset:3072
	v_readlane_b32 s56, v252, 11
	v_readlane_b32 s57, v252, 12
	v_readlane_b32 s58, v252, 13
	v_readlane_b32 s59, v252, 14
	v_readlane_b32 s60, v252, 15
	v_readlane_b32 s61, v252, 16
	v_readlane_b32 s62, v252, 17
	v_readlane_b32 s63, v252, 18
	s_waitcnt vmcnt(15)
	v_mul_f32_e32 v56, v69, v69
	v_mul_f32_e32 v57, v71, v71
	s_waitcnt vmcnt(14)
	v_mul_f32_e32 v58, v73, v73
	v_mul_f32_e32 v59, v75, v75
	s_waitcnt vmcnt(13)
	v_mul_f32_e32 v60, v77, v77
	v_mul_f32_e32 v61, v79, v79
	v_fmac_f32_e32 v56, v68, v68
	v_fmac_f32_e32 v57, v70, v70
	v_fmac_f32_e32 v58, v72, v72
	v_fmac_f32_e32 v59, v74, v74
	s_waitcnt vmcnt(12)
	v_mul_f32_e32 v67, v81, v81
	v_mul_f32_e32 v84, v83, v83
	v_fmac_f32_e32 v60, v76, v76
	v_fmac_f32_e32 v61, v78, v78
	v_add_f32_e32 v56, v56, v57
	v_add_f32_e32 v57, v58, v59
	v_fmac_f32_e32 v67, v80, v80
	v_fmac_f32_e32 v84, v82, v82
	v_add_f32_e32 v58, v60, v61
	v_add_f32_e32 v56, v56, v57
	v_add_f32_e32 v59, v67, v84
	v_add_f32_e32 v56, v56, v58
	v_add_f32_e32 v56, v56, v59
	ds_bpermute_b32 v57, v1, v56
	v_lshl_add_u64 v[58:59], s[46:47], 0, v[54:55]
	v_add_co_u32_e32 v60, vcc, s7, v58
	s_waitcnt lgkmcnt(0)
	v_add_f32_e32 v56, v56, v57
	ds_bpermute_b32 v57, v51, v56
	v_addc_co_u32_e32 v61, vcc, 0, v59, vcc
	s_waitcnt lgkmcnt(0)
	v_add_f32_e32 v56, v56, v57
	ds_bpermute_b32 v57, v62, v56
	s_waitcnt lgkmcnt(0)
	v_add_f32_e32 v67, v56, v57
	ds_bpermute_b32 v84, v63, v67
	v_cvt_pk_bf16_f32 v56, v68, v69
	v_cvt_pk_bf16_f32 v68, v72, v73
	v_cvt_pk_bf16_f32 v57, v70, v71
	v_cvt_pk_bf16_f32 v69, v74, v75
	s_waitcnt lgkmcnt(0)
	v_add_f32_e32 v67, v67, v84
	ds_bpermute_b32 v72, v64, v67
	global_store_dwordx2 v[60:61], v[56:57], off sc1
	global_store_dwordx2 v[60:61], v[68:69], off offset:512 sc1
	v_cvt_pk_bf16_f32 v56, v80, v81
	v_cvt_pk_bf16_f32 v57, v82, v83
	v_cvt_pk_bf16_f32 v70, v76, v77
	s_waitcnt lgkmcnt(0)
	v_add_f32_e32 v67, v67, v72
	ds_bpermute_b32 v68, v65, v67
	v_cvt_pk_bf16_f32 v71, v78, v79
	global_store_dwordx2 v[60:61], v[56:57], off offset:1536 sc1
	v_lshl_add_u64 v[56:57], s[46:47], 0, v[52:53]
	global_store_dwordx2 v[60:61], v[70:71], off offset:1024 sc1
	s_and_saveexec_b64 s[14:15], s[0:1]
	s_cbranch_execz .LBB0_144
	s_waitcnt lgkmcnt(0)
	v_add_f32_e32 v67, v67, v68
	v_add_co_u32_e32 v68, vcc, 0x800000, v56
	v_cndmask_b32_e64 v67, 0, v67, s[4:5]
	s_nop 0
	v_addc_co_u32_e32 v69, vcc, 0, v57, vcc
	global_store_dword v[68:69], v67, off
.LBB0_144:
	s_or_b64 exec, exec, s[14:15]
	s_waitcnt vmcnt(15)
	v_mul_f32_e32 v67, v47, v47
	s_waitcnt lgkmcnt(0)
	v_mul_f32_e32 v68, v49, v49
	v_fmac_f32_e32 v67, v46, v46
	v_fmac_f32_e32 v68, v48, v48
	v_add_f32_e32 v67, v67, v68
	s_waitcnt vmcnt(14)
	v_mul_f32_e32 v68, v43, v43
	v_mul_f32_e32 v69, v45, v45
	v_fmac_f32_e32 v68, v42, v42
	v_fmac_f32_e32 v69, v44, v44
	v_add_f32_e32 v68, v68, v69
	v_add_f32_e32 v67, v67, v68
	s_waitcnt vmcnt(13)
	v_mul_f32_e32 v68, v39, v39
	v_mul_f32_e32 v69, v41, v41
	v_fmac_f32_e32 v68, v38, v38
	v_fmac_f32_e32 v69, v40, v40
	v_add_f32_e32 v68, v68, v69
	v_add_f32_e32 v67, v67, v68
	s_waitcnt vmcnt(12)
	v_mul_f32_e32 v68, v35, v35
	v_mul_f32_e32 v69, v37, v37
	v_fmac_f32_e32 v68, v34, v34
	v_fmac_f32_e32 v69, v36, v36
	v_add_f32_e32 v68, v68, v69
	v_add_f32_e32 v67, v67, v68
	ds_bpermute_b32 v68, v1, v67
	v_cvt_pk_bf16_f32 v46, v46, v47
	v_cvt_pk_bf16_f32 v47, v48, v49
	global_store_dwordx2 v[60:61], v[46:47], off offset:2048 sc1
	v_cvt_pk_bf16_f32 v42, v42, v43
	s_waitcnt lgkmcnt(0)
	v_add_f32_e32 v67, v67, v68
	ds_bpermute_b32 v68, v51, v67
	v_cvt_pk_bf16_f32 v43, v44, v45
	v_cvt_pk_bf16_f32 v38, v38, v39
	v_cvt_pk_bf16_f32 v39, v40, v41
	v_cvt_pk_bf16_f32 v34, v34, v35
	s_waitcnt lgkmcnt(0)
	v_add_f32_e32 v67, v67, v68
	ds_bpermute_b32 v68, v62, v67
	v_cvt_pk_bf16_f32 v35, v36, v37
	global_store_dwordx2 v[60:61], v[42:43], off offset:2560 sc1
	global_store_dwordx2 v[60:61], v[38:39], off offset:3072 sc1
	global_store_dwordx2 v[60:61], v[34:35], off offset:3584 sc1
	s_waitcnt lgkmcnt(0)
	v_add_f32_e32 v67, v67, v68
	ds_bpermute_b32 v68, v63, v67
	s_waitcnt lgkmcnt(0)
	v_add_f32_e32 v67, v67, v68
	ds_bpermute_b32 v68, v64, v67
	s_waitcnt lgkmcnt(0)
	v_add_f32_e32 v46, v67, v68
	ds_bpermute_b32 v47, v65, v46
	s_and_saveexec_b64 s[14:15], s[0:1]
	s_cbranch_execz .LBB0_146
	s_waitcnt lgkmcnt(0)
	v_add_f32_e32 v34, v46, v47
	v_cndmask_b32_e64 v36, 0, v34, s[4:5]
	v_add_co_u32_e32 v34, vcc, 0x800000, v56
	s_nop 1
	v_addc_co_u32_e32 v35, vcc, 0, v57, vcc
	global_store_dword v[34:35], v36, off offset:64
.LBB0_146:
	s_or_b64 exec, exec, s[14:15]
	s_waitcnt vmcnt(15)
	v_mul_f32_e32 v34, v31, v31
	v_mul_f32_e32 v35, v33, v33
	v_fmac_f32_e32 v34, v30, v30
	v_fmac_f32_e32 v35, v32, v32
	v_add_f32_e32 v34, v34, v35
	s_waitcnt vmcnt(14)
	v_mul_f32_e32 v35, v27, v27
	v_mul_f32_e32 v36, v29, v29
	v_fmac_f32_e32 v35, v26, v26
	v_fmac_f32_e32 v36, v28, v28
	v_add_f32_e32 v35, v35, v36
	v_add_f32_e32 v34, v34, v35
	s_waitcnt vmcnt(13)
	v_mul_f32_e32 v35, v23, v23
	v_mul_f32_e32 v36, v25, v25
	v_fmac_f32_e32 v35, v22, v22
	v_fmac_f32_e32 v36, v24, v24
	v_add_f32_e32 v35, v35, v36
	v_add_f32_e32 v34, v34, v35
	s_waitcnt vmcnt(12)
	v_mul_f32_e32 v35, v19, v19
	v_mul_f32_e32 v36, v21, v21
	v_fmac_f32_e32 v35, v18, v18
	v_fmac_f32_e32 v36, v20, v20
	v_add_f32_e32 v35, v35, v36
	v_add_f32_e32 v34, v34, v35
	ds_bpermute_b32 v35, v1, v34
	v_cvt_pk_bf16_f32 v26, v26, v27
	v_cvt_pk_bf16_f32 v27, v28, v29
	v_cvt_pk_bf16_f32 v22, v22, v23
	v_cvt_pk_bf16_f32 v23, v24, v25
	s_waitcnt lgkmcnt(0)
	v_add_f32_e32 v34, v34, v35
	ds_bpermute_b32 v35, v51, v34
	v_cvt_pk_bf16_f32 v18, v18, v19
	v_cvt_pk_bf16_f32 v19, v20, v21
	s_waitcnt lgkmcnt(0)
	v_add_f32_e32 v34, v34, v35
	ds_bpermute_b32 v35, v62, v34
	s_waitcnt lgkmcnt(0)
	v_add_f32_e32 v34, v34, v35
	ds_bpermute_b32 v35, v63, v34
	s_waitcnt lgkmcnt(0)
	v_add_f32_e32 v36, v34, v35
	ds_bpermute_b32 v37, v64, v36
	v_cvt_pk_bf16_f32 v35, v32, v33
	v_cvt_pk_bf16_f32 v34, v30, v31
	v_add_co_u32_e32 v30, vcc, s18, v58
	s_waitcnt lgkmcnt(0)
	v_add_f32_e32 v32, v36, v37
	ds_bpermute_b32 v33, v65, v32
	v_addc_co_u32_e32 v31, vcc, 0, v59, vcc
	global_store_dwordx2 v[30:31], v[34:35], off sc1
	global_store_dwordx2 v[30:31], v[26:27], off offset:512 sc1
	global_store_dwordx2 v[30:31], v[22:23], off offset:1024 sc1
	global_store_dwordx2 v[30:31], v[18:19], off offset:1536 sc1
	s_and_saveexec_b64 s[14:15], s[0:1]
	s_cbranch_execz .LBB0_148
	s_waitcnt lgkmcnt(0)
	v_add_f32_e32 v18, v32, v33
	v_cndmask_b32_e64 v20, 0, v18, s[4:5]
	v_add_co_u32_e32 v18, vcc, 0x800000, v56
	s_nop 1
	v_addc_co_u32_e32 v19, vcc, 0, v57, vcc
	global_store_dword v[18:19], v20, off offset:128
.LBB0_148:
	s_or_b64 exec, exec, s[14:15]
	s_waitcnt vmcnt(15)
	v_mul_f32_e32 v18, v15, v15
	v_mul_f32_e32 v19, v17, v17
	v_fmac_f32_e32 v18, v14, v14
	v_fmac_f32_e32 v19, v16, v16
	v_add_f32_e32 v18, v18, v19
	s_waitcnt vmcnt(14)
	v_mul_f32_e32 v19, v11, v11
	v_mul_f32_e32 v20, v13, v13
	v_fmac_f32_e32 v19, v10, v10
	v_fmac_f32_e32 v20, v12, v12
	v_add_f32_e32 v19, v19, v20
	v_add_f32_e32 v18, v18, v19
	s_waitcnt vmcnt(13)
	v_mul_f32_e32 v19, v7, v7
	v_mul_f32_e32 v20, v9, v9
	v_fmac_f32_e32 v19, v6, v6
	v_fmac_f32_e32 v20, v8, v8
	v_add_f32_e32 v19, v19, v20
	v_add_f32_e32 v18, v18, v19
	s_waitcnt vmcnt(12)
	v_mul_f32_e32 v19, v3, v3
	v_mul_f32_e32 v20, v5, v5
	v_fmac_f32_e32 v19, v2, v2
	v_fmac_f32_e32 v20, v4, v4
	v_add_f32_e32 v19, v19, v20
	v_add_f32_e32 v18, v18, v19
	ds_bpermute_b32 v19, v1, v18
	v_cvt_pk_bf16_f32 v14, v14, v15
	v_cvt_pk_bf16_f32 v15, v16, v17
	global_store_dwordx2 v[30:31], v[14:15], off offset:2048 sc1
	v_cvt_pk_bf16_f32 v10, v10, v11
	s_waitcnt lgkmcnt(0)
	v_add_f32_e32 v18, v18, v19
	ds_bpermute_b32 v19, v51, v18
	v_cvt_pk_bf16_f32 v11, v12, v13
	v_cvt_pk_bf16_f32 v6, v6, v7
	v_cvt_pk_bf16_f32 v7, v8, v9
	v_cvt_pk_bf16_f32 v2, v2, v3
	s_waitcnt lgkmcnt(0)
	v_add_f32_e32 v18, v18, v19
	ds_bpermute_b32 v19, v62, v18
	v_cvt_pk_bf16_f32 v3, v4, v5
	global_store_dwordx2 v[30:31], v[10:11], off offset:2560 sc1
	global_store_dwordx2 v[30:31], v[6:7], off offset:3072 sc1
	global_store_dwordx2 v[30:31], v[2:3], off offset:3584 sc1
	s_waitcnt lgkmcnt(0)
	v_add_f32_e32 v18, v18, v19
	ds_bpermute_b32 v19, v63, v18
	s_waitcnt lgkmcnt(0)
	v_add_f32_e32 v18, v18, v19
	ds_bpermute_b32 v19, v64, v18
	s_waitcnt lgkmcnt(0)
	v_add_f32_e32 v14, v18, v19
	ds_bpermute_b32 v15, v65, v14
	s_and_saveexec_b64 s[14:15], s[0:1]
	s_cbranch_execz .LBB0_141
	s_waitcnt lgkmcnt(0)
	v_add_f32_e32 v2, v14, v15
	v_cndmask_b32_e64 v4, 0, v2, s[4:5]
	v_add_co_u32_e32 v2, vcc, 0x800000, v56
	s_nop 1
	v_addc_co_u32_e32 v3, vcc, 0, v57, vcc
	global_store_dword v[2:3], v4, off offset:192
	s_branch .LBB0_141

.LBB0_243:
	v_lshl_add_u64 v[142:143], s[46:47], 0, v[98:99]
	v_lshl_add_u64 v[146:147], v[142:143], 0, s[0:1]
	v_add_co_u32_e32 v142, vcc, 0x101000, v142
	s_add_i32 s17, s17, -1
	s_nop 0
	v_addc_co_u32_e32 v143, vcc, 0, v143, vcc
	global_load_dwordx4 v[142:145], v[142:143], off
	s_nop 0
	global_load_dwordx4 v[146:149], v[146:147], off offset:16
	v_lshl_add_u64 v[100:101], s[46:47], 0, v[82:83]
	v_lshl_add_u64 v[174:175], s[46:47], 0, v[84:85]
	v_lshl_add_u64 v[176:177], s[46:47], 0, v[86:87]
	v_lshl_add_u64 v[178:179], s[46:47], 0, v[88:89]
	v_lshl_add_u64 v[180:181], s[46:47], 0, v[90:91]
	v_lshl_add_u64 v[182:183], s[46:47], 0, v[92:93]
	v_lshl_add_u64 v[184:185], s[46:47], 0, v[94:95]
	v_lshl_add_u64 v[186:187], s[46:47], 0, v[96:97]
	v_lshl_add_u64 v[82:83], v[82:83], 0, s[4:5]
	v_lshl_add_u64 v[84:85], v[84:85], 0, s[4:5]
	v_lshl_add_u64 v[86:87], v[86:87], 0, s[4:5]
	v_lshl_add_u64 v[88:89], v[88:89], 0, s[4:5]
	v_lshl_add_u64 v[90:91], v[90:91], 0, s[4:5]
	v_lshl_add_u64 v[92:93], v[92:93], 0, s[4:5]
	v_lshl_add_u64 v[94:95], v[94:95], 0, s[4:5]
	v_lshl_add_u64 v[96:97], v[96:97], 0, s[4:5]
	v_lshl_add_u64 v[98:99], v[98:99], 0, s[8:9]
	s_cmp_lg_u32 s17, 0
	s_waitcnt vmcnt(1)
	v_pk_add_f32 v[144:145], v[144:145], 1.0 op_sel_hi:[1,0]
	v_pk_add_f32 v[142:143], v[142:143], 1.0 op_sel_hi:[1,0]
	s_waitcnt vmcnt(0)
	v_pk_add_f32 v[148:149], v[148:149], 1.0 op_sel_hi:[1,0]
	v_pk_add_f32 v[146:147], v[146:147], 1.0 op_sel_hi:[1,0]
	v_pk_mul_f32 v[144:145], v[8:9], v[144:145]
	v_pk_mul_f32 v[142:143], v[6:7], v[142:143]
	v_pk_mul_f32 v[148:149], v[4:5], v[148:149]
	v_pk_mul_f32 v[146:147], v[2:3], v[146:147]
	v_pk_mul_f32 v[150:151], v[56:57], v[142:143]
	v_pk_mul_f32 v[152:153], v[54:55], v[144:145]
	v_pk_mul_f32 v[154:155], v[52:53], v[146:147]
	v_pk_mul_f32 v[156:157], v[50:51], v[148:149]
	v_pk_mul_f32 v[158:159], v[18:19], v[142:143]
	v_pk_mul_f32 v[160:161], v[20:21], v[144:145]
	v_pk_mul_f32 v[162:163], v[22:23], v[146:147]
	v_pk_mul_f32 v[164:165], v[24:25], v[148:149]
	v_pk_mul_f32 v[166:167], v[64:65], v[142:143]
	v_pk_mul_f32 v[168:169], v[62:63], v[144:145]
	v_pk_mul_f32 v[170:171], v[60:61], v[146:147]
	v_pk_mul_f32 v[172:173], v[58:59], v[148:149]
	v_pk_mul_f32 v[188:189], v[26:27], v[142:143]
	v_pk_mul_f32 v[190:191], v[28:29], v[144:145]
	v_pk_mul_f32 v[192:193], v[30:31], v[146:147]
	v_pk_mul_f32 v[194:195], v[32:33], v[148:149]
	v_pk_mul_f32 v[196:197], v[72:73], v[142:143]
	v_pk_mul_f32 v[198:199], v[70:71], v[144:145]
	v_pk_mul_f32 v[200:201], v[68:69], v[146:147]
	v_pk_mul_f32 v[202:203], v[66:67], v[148:149]
	v_pk_mul_f32 v[204:205], v[34:35], v[142:143]
	v_pk_mul_f32 v[206:207], v[36:37], v[144:145]
	v_pk_mul_f32 v[208:209], v[38:39], v[146:147]
	v_pk_mul_f32 v[210:211], v[40:41], v[148:149]
	v_pk_mul_f32 v[212:213], v[80:81], v[142:143]
	v_pk_mul_f32 v[214:215], v[78:79], v[144:145]
	v_pk_mul_f32 v[216:217], v[76:77], v[146:147]
	v_pk_mul_f32 v[218:219], v[74:75], v[148:149]
	v_pk_mul_f32 v[220:221], v[42:43], v[142:143]
	v_pk_mul_f32 v[222:223], v[44:45], v[144:145]
	v_pk_mul_f32 v[224:225], v[46:47], v[146:147]
	v_pk_mul_f32 v[226:227], v[48:49], v[148:149]
	v_cvt_pk_bf16_f32 v142, v150, v151
	v_cvt_pk_bf16_f32 v143, v152, v153
	v_cvt_pk_bf16_f32 v144, v154, v155
	v_cvt_pk_bf16_f32 v145, v156, v157
	v_cvt_pk_bf16_f32 v146, v158, v159
	v_cvt_pk_bf16_f32 v147, v160, v161
	v_cvt_pk_bf16_f32 v148, v162, v163
	v_cvt_pk_bf16_f32 v149, v164, v165
	v_cvt_pk_bf16_f32 v150, v166, v167
	v_cvt_pk_bf16_f32 v151, v168, v169
	v_cvt_pk_bf16_f32 v152, v170, v171
	v_cvt_pk_bf16_f32 v153, v172, v173
	v_cvt_pk_bf16_f32 v154, v188, v189
	v_cvt_pk_bf16_f32 v155, v190, v191
	v_cvt_pk_bf16_f32 v156, v192, v193
	v_cvt_pk_bf16_f32 v157, v194, v195
	v_cvt_pk_bf16_f32 v158, v196, v197
	v_cvt_pk_bf16_f32 v159, v198, v199
	v_cvt_pk_bf16_f32 v160, v200, v201
	v_cvt_pk_bf16_f32 v161, v202, v203
	v_cvt_pk_bf16_f32 v162, v204, v205
	v_cvt_pk_bf16_f32 v163, v206, v207
	v_cvt_pk_bf16_f32 v164, v208, v209
	v_cvt_pk_bf16_f32 v165, v210, v211
	v_cvt_pk_bf16_f32 v166, v212, v213
	v_cvt_pk_bf16_f32 v167, v214, v215
	v_cvt_pk_bf16_f32 v168, v216, v217
	v_cvt_pk_bf16_f32 v169, v218, v219
	v_cvt_pk_bf16_f32 v170, v220, v221
	v_cvt_pk_bf16_f32 v171, v222, v223
	v_cvt_pk_bf16_f32 v172, v224, v225
	v_cvt_pk_bf16_f32 v173, v226, v227
	global_store_dwordx4 v[100:101], v[142:145], off sc1
	global_store_dwordx4 v[174:175], v[146:149], off sc1
	global_store_dwordx4 v[176:177], v[150:153], off sc1
	global_store_dwordx4 v[178:179], v[154:157], off sc1
	global_store_dwordx4 v[180:181], v[158:161], off sc1
	global_store_dwordx4 v[182:183], v[162:165], off sc1
	global_store_dwordx4 v[184:185], v[166:169], off sc1
	global_store_dwordx4 v[186:187], v[170:173], off sc1
	s_cbranch_scc1 .LBB0_243
	s_waitcnt lgkmcnt(0)
	s_add_i32 s14, s14, s15
	s_cmpk_lt_i32 s14, 0x180
	s_cbranch_scc1 .LBB0_242

.LBB0_1315:
	v_add_co_u32_e32 v22, vcc, s14, v18
	v_lshl_add_u64 v[26:27], s[46:47], 0, v[20:21]
	s_nop 0
	v_addc_co_u32_e32 v23, vcc, -1, v19, vcc
	v_add_co_u32_e32 v24, vcc, s15, v18
	s_add_u32 s12, s46, s8
	s_nop 0
	v_addc_co_u32_e32 v25, vcc, -1, v19, vcc
	v_add_co_u32_e32 v28, vcc, s16, v18
	s_addc_u32 s13, s47, s9
	s_nop 0
	v_addc_co_u32_e32 v29, vcc, -1, v19, vcc
	v_add_co_u32_e32 v32, vcc, s1, v26
	s_add_u32 s18, s12, 0x800000
	s_nop 0
	v_addc_co_u32_e32 v33, vcc, 0, v27, vcc
	v_add_co_u32_e32 v26, vcc, s3, v26
	s_addc_u32 s19, s13, 0
	s_nop 0
	v_addc_co_u32_e32 v27, vcc, 0, v27, vcc
	global_load_dwordx2 v[96:97], v[26:27], off offset:-4096
	global_load_dwordx2 v[98:99], v[32:33], off offset:512
	global_load_dwordx2 v[100:101], v[32:33], off offset:1024
	global_load_dwordx2 v[102:103], v[32:33], off offset:1536
	global_load_dwordx2 v[104:105], v[32:33], off offset:2048
	global_load_dwordx2 v[106:107], v[32:33], off offset:2560
	global_load_dwordx2 v[108:109], v[32:33], off offset:3072
	global_load_dwordx2 v[110:111], v[32:33], off offset:3584
	global_load_dwordx2 v[112:113], v[26:27], off
	global_load_dwordx2 v[114:115], v[26:27], off offset:512
	global_load_dwordx2 v[116:117], v[26:27], off offset:1024
	global_load_dwordx2 v[118:119], v[26:27], off offset:1536
	global_load_dwordx2 v[120:121], v[26:27], off offset:2048
	global_load_dwordx4 v[32:35], v0, s[12:13]
	global_load_dwordx4 v[36:39], v0, s[12:13] offset:64
	global_load_dwordx2 v[122:123], v[26:27], off offset:2560
	global_load_dwordx4 v[40:43], v0, s[12:13] offset:128
	global_load_dwordx4 v[44:47], v0, s[12:13] offset:192
	global_load_dwordx2 v[124:125], v[26:27], off offset:3072
	global_load_dwordx2 v[126:127], v[26:27], off offset:3584
	global_load_dwordx4 v[48:51], v1, s[18:19] offset:48
	global_load_dwordx4 v[52:55], v1, s[18:19] offset:32
	global_load_dwordx4 v[56:59], v1, s[18:19] offset:16
	s_add_u32 s18, s12, 0x800040
	s_addc_u32 s19, s13, 0
	global_load_dwordx4 v[60:63], v1, s[18:19] offset:32
	global_load_dwordx4 v[64:67], v1, s[18:19] offset:48
	global_load_dwordx4 v[68:71], v1, s[18:19] offset:16
	s_add_u32 s18, s12, 0x800080
	s_addc_u32 s19, s13, 0
	global_load_dwordx4 v[72:75], v1, s[18:19] offset:48
	global_load_dwordx4 v[76:79], v1, s[18:19] offset:32
	global_load_dwordx4 v[80:83], v1, s[18:19] offset:16
	s_add_u32 s12, s12, 0x8000c0
	s_addc_u32 s13, s13, 0
	global_load_dwordx4 v[84:87], v1, s[12:13] offset:32
	global_load_dwordx4 v[88:91], v1, s[12:13] offset:48
	global_load_dwordx4 v[92:95], v1, s[12:13] offset:16
	s_add_i32 s0, s0, s2
	s_add_u32 s8, s8, s10
	s_addc_u32 s9, s9, s11
	v_lshl_add_u64 v[20:21], v[20:21], 0, s[6:7]
	s_cmp_lt_i32 s0, 0x8000
	s_waitcnt vmcnt(31)
	v_lshlrev_b32_e32 v26, 16, v96
	v_and_b32_e32 v27, 0xffff0000, v96
	v_lshlrev_b32_e32 v96, 16, v97
	v_and_b32_e32 v97, 0xffff0000, v97
	s_waitcnt vmcnt(30)
	v_lshlrev_b32_e32 v128, 16, v98
	v_and_b32_e32 v129, 0xffff0000, v98
	v_lshlrev_b32_e32 v98, 16, v99
	v_and_b32_e32 v99, 0xffff0000, v99
	s_waitcnt vmcnt(29)
	v_lshlrev_b32_e32 v130, 16, v100
	v_and_b32_e32 v131, 0xffff0000, v100
	v_lshlrev_b32_e32 v100, 16, v101
	v_and_b32_e32 v101, 0xffff0000, v101
	s_waitcnt vmcnt(28)
	v_lshlrev_b32_e32 v132, 16, v102
	s_waitcnt vmcnt(10)
	v_pk_add_f32 v[50:51], v[54:55], v[50:51]
	s_waitcnt vmcnt(9)
	v_pk_add_f32 v[34:35], v[34:35], v[58:59]
	v_pk_add_f32 v[32:33], v[32:33], v[56:57]
	v_pk_add_f32 v[48:49], v[52:53], v[48:49]
	v_pk_add_f32 v[34:35], v[34:35], v[50:51]
	v_pk_add_f32 v[32:33], v[32:33], v[48:49]
	v_mov_b32_e32 v49, v34
	v_mov_b32_e32 v48, v33
	v_mov_b32_e32 v33, v35
	s_waitcnt vmcnt(6)
	v_pk_add_f32 v[34:35], v[38:39], v[70:71]
	v_pk_add_f32 v[36:37], v[36:37], v[68:69]
	v_pk_add_f32 v[38:39], v[62:63], v[66:67]
	v_pk_add_f32 v[50:51], v[60:61], v[64:65]
	v_pk_add_f32 v[32:33], v[48:49], v[32:33]
	v_pk_add_f32 v[34:35], v[34:35], v[38:39]
	v_pk_add_f32 v[36:37], v[36:37], v[50:51]
	v_add_f32_e32 v31, v32, v33
	v_mov_b32_e32 v32, v37
	v_mov_b32_e32 v33, v34
	v_mov_b32_e32 v37, v35
	s_waitcnt vmcnt(3)
	v_pk_add_f32 v[34:35], v[42:43], v[82:83]
	v_pk_add_f32 v[38:39], v[40:41], v[80:81]
	v_pk_add_f32 v[40:41], v[78:79], v[74:75]
	v_pk_add_f32 v[42:43], v[76:77], v[72:73]
	v_fmamk_f32 v31, v31, 0x3a800000, v30
	v_pk_add_f32 v[32:33], v[32:33], v[36:37]
	v_pk_add_f32 v[34:35], v[34:35], v[40:41]
	v_pk_add_f32 v[36:37], v[38:39], v[42:43]
	v_rsq_f32_e32 v38, v31
	v_add_f32_e32 v31, v32, v33
	v_mov_b32_e32 v32, v37
	v_mov_b32_e32 v33, v34
	v_mov_b32_e32 v37, v35
	s_waitcnt vmcnt(0)
	v_pk_add_f32 v[34:35], v[46:47], v[94:95]
	v_pk_add_f32 v[40:41], v[44:45], v[92:93]
	v_pk_add_f32 v[42:43], v[86:87], v[90:91]
	v_pk_add_f32 v[44:45], v[84:85], v[88:89]
	v_fmamk_f32 v31, v31, 0x3a800000, v30
	v_pk_add_f32 v[32:33], v[32:33], v[36:37]
	v_pk_add_f32 v[34:35], v[34:35], v[42:43]
	v_pk_add_f32 v[36:37], v[40:41], v[44:45]
	v_rsq_f32_e32 v48, v31
	v_add_f32_e32 v31, v32, v33
	v_mov_b32_e32 v32, v37
	v_mov_b32_e32 v33, v34
	v_mov_b32_e32 v37, v35
	v_fmamk_f32 v31, v31, 0x3a800000, v30
	v_pk_add_f32 v[32:33], v[32:33], v[36:37]
	v_and_b32_e32 v133, 0xffff0000, v102
	v_lshlrev_b32_e32 v102, 16, v103
	v_and_b32_e32 v103, 0xffff0000, v103
	v_rsq_f32_e32 v50, v31
	v_add_f32_e32 v31, v32, v33
	v_pk_mul_f32 v[26:27], v[38:39], v[26:27] op_sel_hi:[0,1]
	v_pk_mul_f32 v[32:33], v[38:39], v[96:97] op_sel_hi:[0,1]
	v_lshlrev_b32_e32 v134, 16, v104
	v_and_b32_e32 v135, 0xffff0000, v104
	v_lshlrev_b32_e32 v104, 16, v105
	v_and_b32_e32 v105, 0xffff0000, v105
	v_pk_mul_f32 v[36:37], v[38:39], v[128:129] op_sel_hi:[0,1]
	v_pk_mul_f32 v[40:41], v[38:39], v[98:99] op_sel_hi:[0,1]
	v_pk_mul_f32 v[44:45], v[38:39], v[130:131] op_sel_hi:[0,1]
	v_pk_mul_f32 v[42:43], v[38:39], v[100:101] op_sel_hi:[0,1]
	v_pk_mul_f32 v[52:53], v[38:39], v[132:133] op_sel_hi:[0,1]
	v_pk_mul_f32 v[46:47], v[38:39], v[102:103] op_sel_hi:[0,1]
	v_fmamk_f32 v31, v31, 0x3a800000, v30
	v_pk_mul_f32 v[34:35], v[4:5], v[32:33]
	v_pk_mul_f32 v[32:33], v[2:3], v[26:27]
	v_lshlrev_b32_e32 v136, 16, v106
	v_and_b32_e32 v137, 0xffff0000, v106
	v_lshlrev_b32_e32 v106, 16, v107
	v_and_b32_e32 v107, 0xffff0000, v107
	v_lshlrev_b32_e32 v138, 16, v108
	v_and_b32_e32 v139, 0xffff0000, v108
	v_lshlrev_b32_e32 v108, 16, v109
	v_and_b32_e32 v109, 0xffff0000, v109
	v_lshlrev_b32_e32 v140, 16, v110
	v_and_b32_e32 v141, 0xffff0000, v110
	v_lshlrev_b32_e32 v110, 16, v111
	v_and_b32_e32 v111, 0xffff0000, v111
	v_pk_mul_f32 v[38:39], v[8:9], v[40:41]
	v_pk_mul_f32 v[36:37], v[6:7], v[36:37]
	v_pk_mul_f32 v[42:43], v[12:13], v[42:43]
	v_pk_mul_f32 v[40:41], v[10:11], v[44:45]
	v_pk_mul_f32 v[46:47], v[16:17], v[46:47]
	v_pk_mul_f32 v[44:45], v[14:15], v[52:53]
	v_rsq_f32_e32 v26, v31
	global_store_dwordx4 v[22:23], v[32:35], off offset:-3072 sc1
	global_store_dwordx4 v[22:23], v[36:39], off offset:-2048 sc1
	global_store_dwordx4 v[22:23], v[40:43], off offset:-1024 sc1
	global_store_dwordx4 v[24:25], v[44:47], off offset:-4096 sc1
	v_pk_mul_f32 v[22:23], v[48:49], v[134:135] op_sel_hi:[0,1]
	v_pk_mul_f32 v[32:33], v[48:49], v[104:105] op_sel_hi:[0,1]
	v_lshlrev_b32_e32 v142, 16, v112
	v_and_b32_e32 v143, 0xffff0000, v112
	v_lshlrev_b32_e32 v112, 16, v113
	v_and_b32_e32 v113, 0xffff0000, v113
	v_pk_mul_f32 v[36:37], v[48:49], v[136:137] op_sel_hi:[0,1]
	v_pk_mul_f32 v[38:39], v[48:49], v[106:107] op_sel_hi:[0,1]
	v_pk_mul_f32 v[40:41], v[48:49], v[138:139] op_sel_hi:[0,1]
	v_pk_mul_f32 v[42:43], v[48:49], v[108:109] op_sel_hi:[0,1]
	v_pk_mul_f32 v[44:45], v[48:49], v[140:141] op_sel_hi:[0,1]
	v_pk_mul_f32 v[46:47], v[48:49], v[110:111] op_sel_hi:[0,1]
	v_pk_mul_f32 v[34:35], v[4:5], v[32:33]
	v_pk_mul_f32 v[32:33], v[2:3], v[22:23]
	v_lshlrev_b32_e32 v144, 16, v114
	v_and_b32_e32 v145, 0xffff0000, v114
	v_lshlrev_b32_e32 v114, 16, v115
	v_and_b32_e32 v115, 0xffff0000, v115
	v_lshlrev_b32_e32 v146, 16, v116
	v_and_b32_e32 v147, 0xffff0000, v116
	v_lshlrev_b32_e32 v116, 16, v117
	v_and_b32_e32 v117, 0xffff0000, v117
	v_lshlrev_b32_e32 v148, 16, v118
	v_and_b32_e32 v149, 0xffff0000, v118
	v_lshlrev_b32_e32 v118, 16, v119
	v_and_b32_e32 v119, 0xffff0000, v119
	v_pk_mul_f32 v[38:39], v[8:9], v[38:39]
	v_pk_mul_f32 v[36:37], v[6:7], v[36:37]
	v_pk_mul_f32 v[42:43], v[12:13], v[42:43]
	v_pk_mul_f32 v[40:41], v[10:11], v[40:41]
	v_pk_mul_f32 v[46:47], v[16:17], v[46:47]
	v_pk_mul_f32 v[44:45], v[14:15], v[44:45]
	global_store_dwordx4 v[24:25], v[32:35], off offset:-3072 sc1
	global_store_dwordx4 v[24:25], v[36:39], off offset:-2048 sc1
	global_store_dwordx4 v[24:25], v[40:43], off offset:-1024 sc1
	global_store_dwordx4 v[24:25], v[44:47], off sc1
	v_pk_mul_f32 v[22:23], v[50:51], v[142:143] op_sel_hi:[0,1]
	v_pk_mul_f32 v[24:25], v[50:51], v[112:113] op_sel_hi:[0,1]
	v_lshlrev_b32_e32 v150, 16, v120
	v_and_b32_e32 v151, 0xffff0000, v120
	v_lshlrev_b32_e32 v120, 16, v121
	v_and_b32_e32 v121, 0xffff0000, v121
	v_pk_mul_f32 v[32:33], v[50:51], v[144:145] op_sel_hi:[0,1]
	v_pk_mul_f32 v[34:35], v[50:51], v[114:115] op_sel_hi:[0,1]
	v_pk_mul_f32 v[36:37], v[50:51], v[146:147] op_sel_hi:[0,1]
	v_pk_mul_f32 v[38:39], v[50:51], v[116:117] op_sel_hi:[0,1]
	v_pk_mul_f32 v[40:41], v[50:51], v[148:149] op_sel_hi:[0,1]
	v_pk_mul_f32 v[42:43], v[50:51], v[118:119] op_sel_hi:[0,1]
	v_pk_mul_f32 v[24:25], v[4:5], v[24:25]
	v_pk_mul_f32 v[22:23], v[2:3], v[22:23]
	v_lshlrev_b32_e32 v152, 16, v122
	v_and_b32_e32 v153, 0xffff0000, v122
	v_lshlrev_b32_e32 v122, 16, v123
	v_and_b32_e32 v123, 0xffff0000, v123
	v_lshlrev_b32_e32 v154, 16, v124
	v_and_b32_e32 v155, 0xffff0000, v124
	v_lshlrev_b32_e32 v124, 16, v125
	v_and_b32_e32 v125, 0xffff0000, v125
	v_lshlrev_b32_e32 v156, 16, v126
	v_and_b32_e32 v157, 0xffff0000, v126
	v_lshlrev_b32_e32 v126, 16, v127
	v_and_b32_e32 v127, 0xffff0000, v127
	v_pk_mul_f32 v[34:35], v[8:9], v[34:35]
	v_pk_mul_f32 v[32:33], v[6:7], v[32:33]
	v_pk_mul_f32 v[38:39], v[12:13], v[38:39]
	v_pk_mul_f32 v[36:37], v[10:11], v[36:37]
	v_pk_mul_f32 v[42:43], v[16:17], v[42:43]
	v_pk_mul_f32 v[40:41], v[14:15], v[40:41]
	global_store_dwordx4 v[28:29], v[22:25], off offset:-3072 sc1
	global_store_dwordx4 v[28:29], v[32:35], off offset:-2048 sc1
	global_store_dwordx4 v[28:29], v[36:39], off offset:-1024 sc1
	global_store_dwordx4 v[18:19], v[40:43], off offset:-4096 sc1
	v_pk_mul_f32 v[22:23], v[26:27], v[150:151] op_sel_hi:[0,1]
	v_pk_mul_f32 v[24:25], v[26:27], v[120:121] op_sel_hi:[0,1]
	v_pk_mul_f32 v[32:33], v[26:27], v[152:153] op_sel_hi:[0,1]
	v_pk_mul_f32 v[28:29], v[26:27], v[122:123] op_sel_hi:[0,1]
	v_pk_mul_f32 v[36:37], v[26:27], v[154:155] op_sel_hi:[0,1]
	v_pk_mul_f32 v[34:35], v[26:27], v[124:125] op_sel_hi:[0,1]
	v_pk_mul_f32 v[40:41], v[26:27], v[156:157] op_sel_hi:[0,1]
	v_pk_mul_f32 v[38:39], v[26:27], v[126:127] op_sel_hi:[0,1]
	v_pk_mul_f32 v[24:25], v[4:5], v[24:25]
	v_pk_mul_f32 v[22:23], v[2:3], v[22:23]
	v_pk_mul_f32 v[28:29], v[8:9], v[28:29]
	v_pk_mul_f32 v[26:27], v[6:7], v[32:33]
	v_pk_mul_f32 v[34:35], v[12:13], v[34:35]
	v_pk_mul_f32 v[32:33], v[10:11], v[36:37]
	v_pk_mul_f32 v[38:39], v[16:17], v[38:39]
	v_pk_mul_f32 v[36:37], v[14:15], v[40:41]
	global_store_dwordx4 v[18:19], v[22:25], off offset:-3072 sc1
	global_store_dwordx4 v[18:19], v[26:29], off offset:-2048 sc1
	global_store_dwordx4 v[18:19], v[32:35], off offset:-1024 sc1
	global_store_dwordx4 v[18:19], v[36:39], off sc1
	v_lshl_add_u64 v[18:19], v[18:19], 0, s[4:5]
	s_cbranch_scc1 .LBB0_1315
